# adds: GEMM whole-line LDS-DMA layout, permlane-swap row max in band softmax, GLA part-1 loads issued together, silu via v_rcp in mem-attention/GLA-2 epilogues
# speedup vs baseline: 1.0096x; 1.0069x over previous
.LBB0_354:
	s_or_b64 exec, exec, s[18:19]
	v_lshl_add_u32 v103, v105, 2, 0
	v_mul_u32_u24_e32 v116, 0x90, v66
	s_waitcnt lgkmcnt(0)
	s_barrier
	ds_read2st64_b32 v[66:67], v103 offset0:106 offset1:107
	v_lshlrev_b32_e32 v117, 16, v100
	v_and_b32_e32 v100, 0xffff0000, v100
	v_mul_f32_e32 v118, 0xbfb8aa3b, v117
	v_mul_f32_e32 v119, 0xbfb8aa3b, v100
	s_waitcnt lgkmcnt(0)
	v_add_f32_e32 v66, v66, v67
	v_fmamk_f32 v66, v66, 0x3c000000, v208
	v_cmp_gt_f32_e32 vcc, s89, v66
	v_mul_f32_e32 v67, 0x4b800000, v66
	v_exp_f32_e32 v118, v118
	v_cndmask_b32_e32 v66, v66, v67, vcc
	v_rsq_f32_e32 v66, v66
	v_exp_f32_e32 v119, v119
	v_readlane_b32 s14, v238, 21
	v_readlane_b32 s15, v238, 22
	v_mul_f32_e32 v67, 0x45800000, v66
	v_pk_add_f32 v[118:119], v[118:119], 1.0 op_sel_hi:[1,0]
	v_cndmask_b32_e32 v68, v66, v67, vcc
	v_or_b32_e32 v66, s14, v105
	v_pk_mul_f32 v[62:63], v[62:63], v[68:69] op_sel_hi:[1,0]
	v_ashrrev_i32_e32 v67, 31, v66
	v_pk_mul_f32 v[62:63], v[14:15], v[62:63]
	v_rcp_f32_e32 v120, v119
	s_nop 0
	v_mul_f32_e32 v119, v100, v120
	v_lshlrev_b64 v[66:67], 12, v[66:67]
	v_pk_mul_f32 v[64:65], v[64:65], v[68:69] op_sel_hi:[1,0]
	v_lshl_add_u64 v[66:67], s[56:57], 0, v[66:67]
	v_rcp_f32_e32 v100, v118
	s_nop 0
	v_mul_f32_e32 v118, v117, v100
	v_pk_mul_f32 v[62:63], v[118:119], v[62:63]
	v_lshlrev_b32_e32 v117, 16, v101
	v_and_b32_e32 v118, 0xffff0000, v101
	v_mul_f32_e32 v100, 0xbfb8aa3b, v117
	v_mul_f32_e32 v101, 0xbfb8aa3b, v118
	v_exp_f32_e32 v100, v100
	v_exp_f32_e32 v101, v101
	v_pk_mul_f32 v[64:65], v[16:17], v[64:65]
	v_lshl_add_u64 v[66:67], v[66:67], 0, s[2:3]
	v_cvt_pk_bf16_f32 v62, v62, v63
	v_pk_add_f32 v[100:101], v[100:101], 1.0 op_sel_hi:[1,0]
	v_pk_mul_f32 v[58:59], v[58:59], v[68:69] op_sel_hi:[1,0]
	v_pk_mul_f32 v[58:59], v[10:11], v[58:59]
	v_pk_mul_f32 v[60:61], v[60:61], v[68:69] op_sel_hi:[1,0]
	s_ashr_i32 s1, s0, 31
	v_rcp_f32_e32 v119, v101
	s_nop 0
	v_mul_f32_e32 v101, v118, v119
	v_pk_mul_f32 v[60:61], v[12:13], v[60:61]
	v_pk_mul_f32 v[54:55], v[54:55], v[68:69] op_sel_hi:[1,0]
	v_pk_mul_f32 v[56:57], v[56:57], v[68:69] op_sel_hi:[1,0]
	v_rcp_f32_e32 v118, v100
	s_nop 0
	v_mul_f32_e32 v100, v117, v118
	v_pk_mul_f32 v[64:65], v[100:101], v[64:65]
	v_pk_mul_f32 v[54:55], v[6:7], v[54:55]
	v_cvt_pk_bf16_f32 v63, v64, v65
	v_lshl_add_u64 v[64:65], v[90:91], 1, v[66:67]
	global_store_dwordx2 v[64:65], v[62:63], off offset:2048
	v_lshlrev_b32_e32 v64, 16, v98
	v_and_b32_e32 v65, 0xffff0000, v98
	v_mul_f32_e32 v62, 0xbfb8aa3b, v64
	v_mul_f32_e32 v63, 0xbfb8aa3b, v65
	v_exp_f32_e32 v62, v62
	v_exp_f32_e32 v63, v63
	v_pk_mul_f32 v[56:57], v[8:9], v[56:57]
	v_pk_mul_f32 v[50:51], v[50:51], v[68:69] op_sel_hi:[1,0]
	v_pk_mul_f32 v[52:53], v[52:53], v[68:69] op_sel_hi:[1,0]
	v_pk_add_f32 v[62:63], v[62:63], 1.0 op_sel_hi:[1,0]
	s_waitcnt vmcnt(13)
	v_pk_mul_f32 v[50:51], v[2:3], v[50:51]
	v_pk_mul_f32 v[52:53], v[4:5], v[52:53]
	v_rcp_f32_e32 v98, v63
	s_nop 0
	v_mul_f32_e32 v63, v65, v98
	s_nop 0
	v_rcp_f32_e32 v65, v62
	s_nop 0
	v_mul_f32_e32 v62, v64, v65
	v_lshlrev_b32_e32 v64, 16, v99
	v_and_b32_e32 v65, 0xffff0000, v99
	v_pk_mul_f32 v[58:59], v[62:63], v[58:59]
	v_mul_f32_e32 v62, 0xbfb8aa3b, v64
	v_mul_f32_e32 v63, 0xbfb8aa3b, v65
	v_exp_f32_e32 v62, v62
	v_exp_f32_e32 v63, v63
	s_nop 0
	v_pk_add_f32 v[62:63], v[62:63], 1.0 op_sel_hi:[1,0]
	s_nop 0
	s_nop 0
	v_rcp_f32_e32 v98, v63
	s_nop 0
	v_mul_f32_e32 v63, v65, v98
	s_nop 0
	v_rcp_f32_e32 v65, v62
	s_nop 0
	v_mul_f32_e32 v62, v64, v65
	v_pk_mul_f32 v[60:61], v[62:63], v[60:61]
	v_cvt_pk_bf16_f32 v62, v58, v59
	v_lshl_add_u64 v[58:59], s[0:1], 0, v[0:1]
	v_cvt_pk_bf16_f32 v63, v60, v61
	v_lshl_add_u64 v[60:61], v[58:59], 1, v[66:67]
	v_lshlrev_b32_e32 v0, 16, v96
	v_and_b32_e32 v64, 0xffff0000, v96
	global_store_dwordx2 v[60:61], v[62:63], off offset:2080
	v_mul_f32_e32 v62, 0xbfb8aa3b, v0
	v_mul_f32_e32 v63, 0xbfb8aa3b, v64
	v_exp_f32_e32 v62, v62
	v_exp_f32_e32 v63, v63
	s_nop 0
	v_pk_add_f32 v[62:63], v[62:63], 1.0 op_sel_hi:[1,0]
	s_nop 0
	s_nop 0
	v_rcp_f32_e32 v65, v63
	s_nop 0
	v_mul_f32_e32 v63, v64, v65
	s_nop 0
	v_rcp_f32_e32 v64, v62
	s_nop 0
	v_mul_f32_e32 v62, v0, v64
	v_lshlrev_b32_e32 v0, 16, v97
	v_and_b32_e32 v64, 0xffff0000, v97
	v_pk_mul_f32 v[54:55], v[62:63], v[54:55]
	v_mul_f32_e32 v62, 0xbfb8aa3b, v0
	v_mul_f32_e32 v63, 0xbfb8aa3b, v64
	v_exp_f32_e32 v62, v62
	v_exp_f32_e32 v63, v63
	v_cvt_pk_bf16_f32 v54, v54, v55
	v_pk_add_f32 v[62:63], v[62:63], 1.0 op_sel_hi:[1,0]
	s_nop 0
	s_nop 0
	v_rcp_f32_e32 v65, v63
	s_nop 0
	v_mul_f32_e32 v63, v64, v65
	s_nop 0
	v_rcp_f32_e32 v64, v62
	s_nop 0
	v_mul_f32_e32 v62, v0, v64
	v_pk_mul_f32 v[56:57], v[62:63], v[56:57]
	v_lshlrev_b32_e32 v0, 16, v94
	v_cvt_pk_bf16_f32 v55, v56, v57
	v_and_b32_e32 v56, 0xffff0000, v94
	global_store_dwordx2 v[60:61], v[54:55], off offset:2112
	v_mul_f32_e32 v54, 0xbfb8aa3b, v0
	v_mul_f32_e32 v55, 0xbfb8aa3b, v56
	v_exp_f32_e32 v54, v54
	v_exp_f32_e32 v55, v55
	s_nop 0
	v_pk_add_f32 v[54:55], v[54:55], 1.0 op_sel_hi:[1,0]
	s_nop 0
	s_nop 0
	v_rcp_f32_e32 v57, v55
	s_nop 0
	v_mul_f32_e32 v55, v56, v57
	s_nop 0
	v_rcp_f32_e32 v56, v54
	s_nop 0
	v_mul_f32_e32 v54, v0, v56
	v_lshlrev_b32_e32 v0, 16, v95
	v_and_b32_e32 v56, 0xffff0000, v95
	v_pk_mul_f32 v[50:51], v[54:55], v[50:51]
	v_mul_f32_e32 v54, 0xbfb8aa3b, v0
	v_mul_f32_e32 v55, 0xbfb8aa3b, v56
	v_exp_f32_e32 v54, v54
	v_exp_f32_e32 v55, v55
	v_cvt_pk_bf16_f32 v50, v50, v51
	v_pk_add_f32 v[54:55], v[54:55], 1.0 op_sel_hi:[1,0]
	s_nop 0
	s_nop 0
	v_rcp_f32_e32 v57, v55
	s_nop 0
	v_mul_f32_e32 v55, v56, v57
	v_div_scale_f32 v56, s[0:1], v54, v54, v0
	v_rcp_f32_e32 v57, v56
	s_mov_b32 s0, 0x3e000000
	s_waitcnt vmcnt(14)
	v_and_b32_e32 v63, 0xffff0000, v40
	v_fma_f32 v60, -v56, v57, 1.0
	v_fmac_f32_e32 v57, v60, v57
	v_div_scale_f32 v60, vcc, v0, v54, v0
	v_mul_f32_e32 v61, v60, v57
	v_fma_f32 v62, -v56, v61, v60
	v_fmac_f32_e32 v61, v62, v57
	v_fma_f32 v56, -v56, v61, v60
	v_div_fmas_f32 v56, v56, v57, v61
	v_div_fixup_f32 v54, v56, v54, v0
	v_pk_mul_f32 v[52:53], v[54:55], v[52:53]
	s_waitcnt vmcnt(11)
	v_mul_f32_e32 v0, 0x3fb8aa3b, v46
	v_cvt_pk_bf16_f32 v51, v52, v53
	v_lshl_add_u64 v[52:53], v[82:83], 1, v[66:67]
	global_store_dwordx2 v[52:53], v[50:51], off offset:2048
	v_exp_f32_e32 v50, v0
	v_mul_f32_e32 v0, 0xbfb8aa3b, v46
	v_exp_f32_e32 v46, v0
	v_mul_f32_e32 v0, 0x3fb8aa3b, v47
	v_exp_f32_e32 v51, v0
	v_mul_f32_e32 v0, 0xbfb8aa3b, v47
	v_exp_f32_e32 v47, v0
	v_lshlrev_b32_e32 v52, 16, v38
	v_and_b32_e32 v53, 0xffff0000, v38
	v_pk_mul_f32 v[52:53], v[52:53], s[0:1] op_sel_hi:[1,0]
	v_lshlrev_b32_e32 v56, 16, v30
	v_and_b32_e32 v57, 0xffff0000, v30
	v_mul_f32_e32 v0, 0x3fb8aa3b, v48
	v_pk_mul_f32 v[54:55], v[52:53], v[50:51]
	v_pk_mul_f32 v[52:53], v[52:53], v[46:47]
	v_pk_mul_f32 v[50:51], v[50:51], v[56:57]
	v_pk_mul_f32 v[46:47], v[46:47], v[56:57]
	v_exp_f32_e32 v56, v0
	v_mul_f32_e32 v0, 0xbfb8aa3b, v48
	v_exp_f32_e32 v48, v0
	v_mul_f32_e32 v0, 0x3fb8aa3b, v49
	v_exp_f32_e32 v57, v0
	v_mul_f32_e32 v0, 0xbfb8aa3b, v49
	v_exp_f32_e32 v49, v0
	v_lshlrev_b32_e32 v38, 16, v39
	v_and_b32_e32 v39, 0xffff0000, v39
	v_pk_mul_f32 v[38:39], v[38:39], s[0:1] op_sel_hi:[1,0]
	v_lshlrev_b32_e32 v30, 16, v31
	v_and_b32_e32 v31, 0xffff0000, v31
	v_mul_f32_e32 v0, 0x3fb8aa3b, v42
	v_pk_mul_f32 v[60:61], v[38:39], v[56:57]
	v_pk_mul_f32 v[38:39], v[38:39], v[48:49]
	v_pk_mul_f32 v[56:57], v[56:57], v[30:31]
	v_pk_mul_f32 v[48:49], v[48:49], v[30:31]
	v_exp_f32_e32 v30, v0
	v_mul_f32_e32 v0, 0xbfb8aa3b, v42
	v_exp_f32_e32 v42, v0
	v_mul_f32_e32 v0, 0x3fb8aa3b, v43
	v_exp_f32_e32 v31, v0
	v_mul_f32_e32 v0, 0xbfb8aa3b, v43
	v_lshlrev_b32_e32 v62, 16, v40
	v_exp_f32_e32 v43, v0
	v_pk_mul_f32 v[62:63], v[62:63], s[0:1] op_sel_hi:[1,0]
	v_lshlrev_b32_e32 v66, 16, v32
	v_and_b32_e32 v67, 0xffff0000, v32
	v_mul_f32_e32 v0, 0x3fb8aa3b, v44
	v_pk_mul_f32 v[64:65], v[62:63], v[30:31]
	v_pk_mul_f32 v[94:95], v[30:31], v[66:67]
	v_exp_f32_e32 v30, v0
	v_mul_f32_e32 v0, 0xbfb8aa3b, v44
	v_exp_f32_e32 v44, v0
	v_mul_f32_e32 v0, 0x3fb8aa3b, v45
	v_exp_f32_e32 v31, v0
	v_mul_f32_e32 v0, 0xbfb8aa3b, v45
	v_exp_f32_e32 v45, v0
	v_lshlrev_b32_e32 v40, 16, v41
	v_and_b32_e32 v41, 0xffff0000, v41
	v_pk_mul_f32 v[40:41], v[40:41], s[0:1] op_sel_hi:[1,0]
	v_pk_mul_f32 v[62:63], v[62:63], v[42:43]
	v_pk_mul_f32 v[42:43], v[42:43], v[66:67]
	v_pk_mul_f32 v[66:67], v[40:41], v[30:31]
	v_lshlrev_b32_e32 v32, 16, v33
	v_and_b32_e32 v33, 0xffff0000, v33
	v_pk_mul_f32 v[40:41], v[40:41], v[44:45]
	v_pk_mul_f32 v[96:97], v[30:31], v[32:33]
	v_pk_mul_f32 v[44:45], v[44:45], v[32:33]
	v_cvt_pk_bf16_f32 v30, v54, v55
	v_cvt_pk_bf16_f32 v31, v60, v61
	v_cvt_pk_bf16_f32 v32, v64, v65
	v_cvt_pk_bf16_f32 v33, v66, v67
	s_barrier
	ds_write_b128 v74, v[30:33] offset:27648
	v_cvt_pk_bf16_f32 v30, v52, v53
	v_cvt_pk_bf16_f32 v31, v38, v39
	v_cvt_pk_bf16_f32 v32, v62, v63
	v_cvt_pk_bf16_f32 v33, v40, v41
	ds_write_b128 v74, v[30:33] offset:36864
	v_cvt_pk_bf16_f32 v30, v50, v51
	v_cvt_pk_bf16_f32 v31, v56, v57
	v_cvt_pk_bf16_f32 v32, v94, v95
	v_cvt_pk_bf16_f32 v33, v96, v97
	ds_write_b128 v74, v[30:33] offset:46080
	v_cvt_pk_bf16_f32 v30, v46, v47
	v_cvt_pk_bf16_f32 v31, v48, v49
	v_cvt_pk_bf16_f32 v32, v42, v43
	v_cvt_pk_bf16_f32 v33, v44, v45
	ds_write_b128 v74, v[30:33] offset:55296
	s_waitcnt vmcnt(11)
	ds_write_b128 v75, v[18:21]
	s_waitcnt vmcnt(10)
	ds_write_b128 v76, v[22:25]
	s_waitcnt vmcnt(9)
	ds_write_b128 v77, v[26:29]
	s_waitcnt vmcnt(8)
	ds_write_b128 v78, v[34:37]
	s_waitcnt lgkmcnt(0)
	s_barrier
	ds_read_b128 v[18:21], v69 offset:27648
	v_add_u32_e32 v0, v70, v116
	ds_read_b128 v[22:25], v0 offset:55296
	s_waitcnt lgkmcnt(0)
	v_mfma_f32_16x16x32_bf16 v[18:21], v[18:21], v[22:25], 0
	ds_read_b128 v[22:25], v69 offset:36864
	ds_read_b128 v[26:29], v0 offset:46080
	s_waitcnt lgkmcnt(0)
	v_mfma_f32_16x16x32_bf16 v[22:25], v[22:25], v[26:29], 0
	ds_read_b128 v[26:29], v69 offset:27712
	ds_read_b128 v[30:33], v0 offset:55360
	s_waitcnt lgkmcnt(0)
	v_mfma_f32_16x16x32_bf16 v[18:21], v[26:29], v[30:33], v[18:21]
	ds_read_b128 v[26:29], v69 offset:36928
	ds_read_b128 v[30:33], v0 offset:46144
	s_waitcnt lgkmcnt(0)
	v_mfma_f32_16x16x32_bf16 v[22:25], v[26:29], v[30:33], v[22:25]
	s_nop 7
	v_cndmask_b32_e64 v18, v18, v22, s[38:39]
	v_cvt_pk_bf16_f32 v18, v18, s0
	ds_write_b16 v71, v18
	v_cndmask_b32_e64 v18, v19, v23, s[40:41]
	v_cvt_pk_bf16_f32 v18, v18, s0
	ds_write_b16 v71, v18 offset:144
	v_cndmask_b32_e64 v18, v20, v24, s[42:43]
	v_cvt_pk_bf16_f32 v18, v18, s0
	ds_write_b16 v71, v18 offset:288
	v_cndmask_b32_e64 v18, v21, v25, s[44:45]
	v_cvt_pk_bf16_f32 v18, v18, s0
	ds_write_b16 v71, v18 offset:432
	ds_read_b128 v[18:21], v69 offset:27648
	ds_read_b128 v[22:25], v0 offset:57600
	s_waitcnt lgkmcnt(0)
	v_mfma_f32_16x16x32_bf16 v[18:21], v[18:21], v[22:25], 0
	ds_read_b128 v[22:25], v69 offset:36864
	ds_read_b128 v[26:29], v0 offset:48384
	s_waitcnt lgkmcnt(0)
	v_mfma_f32_16x16x32_bf16 v[22:25], v[22:25], v[26:29], 0
	ds_read_b128 v[26:29], v69 offset:27712
	ds_read_b128 v[30:33], v0 offset:57664
	s_waitcnt lgkmcnt(0)
	v_mfma_f32_16x16x32_bf16 v[18:21], v[26:29], v[30:33], v[18:21]
	ds_read_b128 v[26:29], v69 offset:36928
	ds_read_b128 v[30:33], v0 offset:48448
	s_waitcnt lgkmcnt(0)
	v_mfma_f32_16x16x32_bf16 v[22:25], v[26:29], v[30:33], v[22:25]
	s_nop 7
	v_cndmask_b32_e64 v0, v18, v22, s[46:47]
	v_cvt_pk_bf16_f32 v0, v0, s0
	ds_write_b16 v79, v0
	v_cndmask_b32_e64 v0, v19, v23, s[48:49]
	v_cvt_pk_bf16_f32 v0, v0, s0
	ds_write_b16 v81, v0
	v_cndmask_b32_e64 v0, v20, v24, s[50:51]
	v_cvt_pk_bf16_f32 v0, v0, s0
	ds_write_b16 v104, v0
	v_cndmask_b32_e64 v0, v21, v25, s[52:53]
	v_cvt_pk_bf16_f32 v0, v0, s0
	ds_write_b16 v106, v0
	s_waitcnt lgkmcnt(0)
	s_barrier
	ds_read_b128 v[18:21], v107
	ds_read_b128 v[34:37], v73
	ds_read_b128 v[22:25], v80
	ds_read_b128 v[38:41], v72 offset:27648
	s_waitcnt lgkmcnt(2)
	v_mfma_f32_16x16x32_bf16 v[18:21], v[18:21], v[34:37], 0
	s_waitcnt lgkmcnt(0)
	v_mfma_f32_16x16x32_bf16 v[18:21], v[22:25], v[38:41], v[18:21]
	ds_read_b128 v[22:25], v107 offset:64
	ds_read_b128 v[42:45], v73 offset:64
	s_waitcnt lgkmcnt(0)
	v_mfma_f32_16x16x32_bf16 v[18:21], v[22:25], v[42:45], v[18:21]
	ds_read_b128 v[22:25], v80 offset:64
	ds_read_b128 v[46:49], v72 offset:27712
	s_waitcnt lgkmcnt(0)
	v_mfma_f32_16x16x32_bf16 v[30:33], v[22:25], v[46:49], v[18:21]
	ds_read_b128 v[22:25], v108
	s_nop 2
	ds_read_b128 v[18:21], v109
	s_waitcnt lgkmcnt(0)
	v_mfma_f32_16x16x32_bf16 v[18:21], v[18:21], v[34:37], 0
	s_nop 0
	v_mul_f32_e32 v0, v31, v31
	v_fmac_f32_e32 v0, v30, v30
	v_mfma_f32_16x16x32_bf16 v[18:21], v[22:25], v[38:41], v[18:21]
	ds_read_b128 v[22:25], v109 offset:64
	s_waitcnt lgkmcnt(0)
	v_mfma_f32_16x16x32_bf16 v[18:21], v[22:25], v[42:45], v[18:21]
	ds_read_b128 v[22:25], v108 offset:64
	s_waitcnt lgkmcnt(0)
	v_mfma_f32_16x16x32_bf16 v[26:29], v[22:25], v[46:49], v[18:21]
	s_nop 4
	ds_read_b128 v[18:21], v111
	ds_read_b128 v[22:25], v110
	s_waitcnt lgkmcnt(1)
	v_mfma_f32_16x16x32_bf16 v[18:21], v[18:21], v[34:37], 0
	s_waitcnt lgkmcnt(0)
	v_mfma_f32_16x16x32_bf16 v[18:21], v[22:25], v[38:41], v[18:21]
	ds_read_b128 v[22:25], v111 offset:64
	s_waitcnt lgkmcnt(0)
	v_mfma_f32_16x16x32_bf16 v[18:21], v[22:25], v[42:45], v[18:21]
	ds_read_b128 v[22:25], v110 offset:64
	s_waitcnt lgkmcnt(0)
	v_mfma_f32_16x16x32_bf16 v[22:25], v[22:25], v[46:49], v[18:21]
	s_nop 4
	ds_read_b128 v[18:21], v113
	s_waitcnt lgkmcnt(0)
	v_mfma_f32_16x16x32_bf16 v[18:21], v[18:21], v[34:37], 0
	ds_read_b128 v[34:37], v112
	s_waitcnt lgkmcnt(0)
	v_mfma_f32_16x16x32_bf16 v[18:21], v[34:37], v[38:41], v[18:21]
	ds_read_b128 v[34:37], v113 offset:64
	s_waitcnt lgkmcnt(0)
	v_mfma_f32_16x16x32_bf16 v[18:21], v[34:37], v[42:45], v[18:21]
	ds_read_b128 v[34:37], v112 offset:64
	s_waitcnt lgkmcnt(0)
	v_mfma_f32_16x16x32_bf16 v[18:21], v[34:37], v[46:49], v[18:21]
	v_mul_f32_e32 v34, v33, v33
	v_fmac_f32_e32 v34, v32, v32
	v_add_f32_e32 v0, v0, v34
	v_mul_f32_e32 v34, v27, v27
	v_mul_f32_e32 v35, v29, v29
	v_fmac_f32_e32 v34, v26, v26
	v_fmac_f32_e32 v35, v28, v28
	v_add_f32_e32 v34, v34, v35
	v_add_f32_e32 v0, v0, v34
	v_mul_f32_e32 v34, v23, v23
	v_mul_f32_e32 v35, v25, v25
	v_fmac_f32_e32 v34, v22, v22
	v_fmac_f32_e32 v35, v24, v24
	v_add_f32_e32 v34, v34, v35
	v_add_f32_e32 v0, v0, v34
	v_mul_f32_e32 v34, v19, v19
	v_mul_f32_e32 v35, v21, v21
	v_fmac_f32_e32 v34, v18, v18
	v_fmac_f32_e32 v35, v20, v20
	v_add_f32_e32 v34, v34, v35
	v_add_f32_e32 v0, v0, v34
	ds_bpermute_b32 v34, v114, v0
	s_waitcnt lgkmcnt(0)
	v_add_f32_e32 v0, v0, v34
	ds_bpermute_b32 v34, v115, v0
	s_and_saveexec_b64 s[0:1], s[54:55]
	s_cbranch_execz .LBB0_356
	s_and_b32 s14, s77, 0xffffff00
	s_add_i32 s14, s14, 0
	s_lshl_b32 s15, s79, 2
	s_add_i32 s14, s14, s15
	s_waitcnt lgkmcnt(0)
	v_add_f32_e32 v0, v0, v34
	v_lshl_add_u32 v34, v102, 2, s14
	ds_write_b32 v34, v0 offset:27136
.LBB0_356:
	s_or_b64 exec, exec, s[0:1]
	s_waitcnt lgkmcnt(0)
	s_barrier
	ds_read2st64_b32 v[34:35], v103 offset0:106 offset1:107
	s_waitcnt vmcnt(7)
	v_lshlrev_b32_e32 v38, 16, v92
	v_and_b32_e32 v39, 0xffff0000, v92
	v_mul_f32_e32 v36, 0xbfb8aa3b, v38
	v_exp_f32_e32 v36, v36
	s_waitcnt lgkmcnt(0)
	v_add_f32_e32 v0, v34, v35
	v_fmamk_f32 v0, v0, 0x3c000000, v208
	v_cmp_gt_f32_e32 vcc, s89, v0
	v_mul_f32_e32 v34, 0x4b800000, v0
	v_readlane_b32 s0, v238, 28
	v_cndmask_b32_e32 v0, v0, v34, vcc
	v_rsq_f32_e32 v0, v0
	v_readlane_b32 s1, v238, 29
	v_mul_f32_e32 v34, 0x45800000, v0
	v_cndmask_b32_e32 v0, v0, v34, vcc
	v_pk_mul_f32 v[30:31], v[30:31], v[0:1] op_sel_hi:[1,0]
	v_or_b32_e32 v34, s0, v105
	v_pk_mul_f32 v[14:15], v[14:15], v[30:31]
	v_mul_f32_e32 v30, 0xbfb8aa3b, v39
	v_exp_f32_e32 v37, v30
	v_pk_mul_f32 v[32:33], v[32:33], v[0:1] op_sel_hi:[1,0]
	v_ashrrev_i32_e32 v35, 31, v34
	v_pk_mul_f32 v[16:17], v[16:17], v[32:33]
	v_pk_add_f32 v[30:31], v[36:37], 1.0 op_sel_hi:[1,0]
	v_lshlrev_b64 v[34:35], 12, v[34:35]
	v_lshl_add_u64 v[34:35], s[56:57], 0, v[34:35]
	v_lshl_add_u64 v[34:35], v[34:35], 0, s[2:3]
	v_rcp_f32_e32 v36, v31
	s_nop 0
	v_mul_f32_e32 v31, v39, v36
	s_nop 0
	v_rcp_f32_e32 v36, v30
	s_nop 0
	v_mul_f32_e32 v30, v38, v36
	v_lshlrev_b32_e32 v36, 16, v93
	v_and_b32_e32 v37, 0xffff0000, v93
	v_pk_mul_f32 v[14:15], v[30:31], v[14:15]
	v_mul_f32_e32 v30, 0xbfb8aa3b, v36
	v_mul_f32_e32 v31, 0xbfb8aa3b, v37
	v_exp_f32_e32 v30, v30
	v_exp_f32_e32 v31, v31
	v_cvt_pk_bf16_f32 v14, v14, v15
	v_pk_add_f32 v[30:31], v[30:31], 1.0 op_sel_hi:[1,0]
	s_nop 0
	s_nop 0
	v_rcp_f32_e32 v32, v31
	s_nop 0
	v_mul_f32_e32 v31, v37, v32
	s_nop 0
	v_rcp_f32_e32 v32, v30
	s_nop 0
	v_mul_f32_e32 v30, v36, v32
	v_pk_mul_f32 v[16:17], v[30:31], v[16:17]
	s_waitcnt vmcnt(6)
	v_lshlrev_b32_e32 v30, 16, v88
	v_cvt_pk_bf16_f32 v15, v16, v17
	v_lshl_add_u64 v[16:17], v[90:91], 1, v[34:35]
	v_and_b32_e32 v31, 0xffff0000, v88
	global_store_dwordx2 v[16:17], v[14:15], off offset:2048
	v_mul_f32_e32 v14, 0xbfb8aa3b, v30
	v_mul_f32_e32 v15, 0xbfb8aa3b, v31
	v_exp_f32_e32 v14, v14
	v_exp_f32_e32 v15, v15
	v_pk_mul_f32 v[16:17], v[26:27], v[0:1] op_sel_hi:[1,0]
	v_pk_add_f32 v[14:15], v[14:15], 1.0 op_sel_hi:[1,0]
	v_pk_mul_f32 v[10:11], v[10:11], v[16:17]
	s_nop 0
	v_rcp_f32_e32 v16, v15
	s_nop 0
	v_mul_f32_e32 v15, v31, v16
	s_nop 0
	v_rcp_f32_e32 v16, v14
	s_nop 0
	v_mul_f32_e32 v14, v30, v16
	v_lshlrev_b32_e32 v26, 16, v89
	v_and_b32_e32 v27, 0xffff0000, v89
	v_pk_mul_f32 v[10:11], v[14:15], v[10:11]
	v_mul_f32_e32 v14, 0xbfb8aa3b, v26
	v_mul_f32_e32 v15, 0xbfb8aa3b, v27
	v_exp_f32_e32 v14, v14
	v_exp_f32_e32 v15, v15
	v_pk_mul_f32 v[16:17], v[28:29], v[0:1] op_sel_hi:[1,0]
	v_cvt_pk_bf16_f32 v10, v10, v11
	v_pk_mul_f32 v[12:13], v[12:13], v[16:17]
	v_pk_add_f32 v[14:15], v[14:15], 1.0 op_sel_hi:[1,0]
	s_nop 0
	s_nop 0
	v_rcp_f32_e32 v16, v15
	s_nop 0
	v_mul_f32_e32 v15, v27, v16
	s_nop 0
	v_rcp_f32_e32 v16, v14
	s_nop 0
	v_mul_f32_e32 v14, v26, v16
	v_pk_mul_f32 v[12:13], v[14:15], v[12:13]
	s_waitcnt vmcnt(6)
	v_lshlrev_b32_e32 v16, 16, v86
	v_cvt_pk_bf16_f32 v11, v12, v13
	v_lshl_add_u64 v[12:13], v[58:59], 1, v[34:35]
	v_and_b32_e32 v17, 0xffff0000, v86
	global_store_dwordx2 v[12:13], v[10:11], off offset:2080
	v_mul_f32_e32 v10, 0xbfb8aa3b, v16
	v_mul_f32_e32 v11, 0xbfb8aa3b, v17
	v_exp_f32_e32 v10, v10
	v_exp_f32_e32 v11, v11
	v_pk_mul_f32 v[14:15], v[22:23], v[0:1] op_sel_hi:[1,0]
	v_pk_add_f32 v[10:11], v[10:11], 1.0 op_sel_hi:[1,0]
	v_pk_mul_f32 v[6:7], v[6:7], v[14:15]
	s_nop 0
	v_rcp_f32_e32 v14, v11
	s_nop 0
	v_mul_f32_e32 v11, v17, v14
	s_nop 0
	v_rcp_f32_e32 v14, v10
	s_nop 0
	v_mul_f32_e32 v10, v16, v14
	v_lshlrev_b32_e32 v16, 16, v87
	v_and_b32_e32 v17, 0xffff0000, v87
	v_pk_mul_f32 v[6:7], v[10:11], v[6:7]
	v_mul_f32_e32 v10, 0xbfb8aa3b, v16
	v_mul_f32_e32 v11, 0xbfb8aa3b, v17
	v_exp_f32_e32 v10, v10
	v_exp_f32_e32 v11, v11
	v_pk_mul_f32 v[14:15], v[24:25], v[0:1] op_sel_hi:[1,0]
	v_cvt_pk_bf16_f32 v6, v6, v7
	v_pk_mul_f32 v[8:9], v[8:9], v[14:15]
	v_pk_add_f32 v[10:11], v[10:11], 1.0 op_sel_hi:[1,0]
	s_nop 0
	s_nop 0
	v_rcp_f32_e32 v14, v11
	s_nop 0
	v_mul_f32_e32 v11, v17, v14
	s_nop 0
	v_rcp_f32_e32 v14, v10
	s_nop 0
	v_mul_f32_e32 v10, v16, v14
	v_pk_mul_f32 v[8:9], v[10:11], v[8:9]
	s_waitcnt vmcnt(6)
	v_lshlrev_b32_e32 v10, 16, v84
	v_cvt_pk_bf16_f32 v7, v8, v9
	v_and_b32_e32 v11, 0xffff0000, v84
	global_store_dwordx2 v[12:13], v[6:7], off offset:2112
	v_mul_f32_e32 v6, 0xbfb8aa3b, v10
	v_mul_f32_e32 v7, 0xbfb8aa3b, v11
	v_exp_f32_e32 v6, v6
	v_exp_f32_e32 v7, v7
	v_pk_mul_f32 v[8:9], v[18:19], v[0:1] op_sel_hi:[1,0]
	v_pk_add_f32 v[6:7], v[6:7], 1.0 op_sel_hi:[1,0]
	v_pk_mul_f32 v[2:3], v[2:3], v[8:9]
	s_nop 0
	v_rcp_f32_e32 v8, v7
	s_nop 0
	v_mul_f32_e32 v7, v11, v8
	s_nop 0
	v_rcp_f32_e32 v8, v6
	s_nop 0
	v_mul_f32_e32 v6, v10, v8
	v_lshlrev_b32_e32 v10, 16, v85
	v_and_b32_e32 v11, 0xffff0000, v85
	v_pk_mul_f32 v[2:3], v[6:7], v[2:3]
	v_mul_f32_e32 v6, 0xbfb8aa3b, v10
	v_pk_mul_f32 v[8:9], v[20:21], v[0:1] op_sel_hi:[1,0]
	v_mul_f32_e32 v0, 0xbfb8aa3b, v11
	v_exp_f32_e32 v6, v6
	v_exp_f32_e32 v7, v0
	v_pk_mul_f32 v[4:5], v[4:5], v[8:9]
	v_cvt_pk_bf16_f32 v2, v2, v3
	v_pk_add_f32 v[6:7], v[6:7], 1.0 op_sel_hi:[1,0]
	s_nop 0
	s_nop 0
	v_rcp_f32_e32 v0, v7
	s_nop 0
	v_mul_f32_e32 v7, v11, v0
	s_nop 0
	v_rcp_f32_e32 v0, v6
	s_nop 0
	v_mul_f32_e32 v6, v10, v0
	v_pk_mul_f32 v[4:5], v[6:7], v[4:5]
	s_nop 0
	v_cvt_pk_bf16_f32 v3, v4, v5
	v_lshl_add_u64 v[4:5], v[82:83], 1, v[34:35]
	global_store_dwordx2 v[4:5], v[2:3], off offset:2048
	s_barrier

.LBB0_396:
	v_min_i32_e32 v171, 0x80, v227
	v_min_i32_e32 v172, 0x82, v234
	v_min_i32_e32 v173, 0x83, v234
	v_min_i32_e32 v174, 0x90, v234
	v_min_i32_e32 v175, 0x91, v234
	v_min_i32_e32 v176, 0x92, v234
	v_min_i32_e32 v177, 0x93, v234
	v_lshl_add_u32 v170, v199, 2, s14
	v_lshl_add_u32 v171, v171, 2, s14
	v_lshl_add_u32 v172, v172, 2, s14
	v_lshl_add_u32 v173, v173, 2, s14
	v_lshl_add_u32 v174, v174, 2, s14
	v_lshl_add_u32 v175, v175, 2, s14
	v_lshl_add_u32 v176, v176, 2, s14
	v_lshl_add_u32 v177, v177, 2, s14
	ds_read_b32 v170, v170 offset:512
	ds_read_b32 v171, v171 offset:512
	ds_read_b32 v172, v172 offset:504
	ds_read_b32 v173, v173 offset:500
	ds_read_b32 v174, v174 offset:448
	ds_read_b32 v175, v175 offset:444
	ds_read_b32 v176, v176 offset:440
	ds_read_b32 v177, v177 offset:436
	v_min_i32_e32 v178, 0xa0, v234
	v_min_i32_e32 v179, 0xa1, v234
	v_min_i32_e32 v180, 0xa2, v234
	v_min_i32_e32 v181, 0xa3, v234
	v_min_i32_e32 v182, 0xb0, v234
	v_min_i32_e32 v183, 0xb1, v234
	v_min_i32_e32 v184, 0xb2, v234
	v_min_i32_e32 v185, 0xb3, v234
	v_lshl_add_u32 v178, v178, 2, s14
	v_lshl_add_u32 v179, v179, 2, s14
	v_lshl_add_u32 v180, v180, 2, s14
	v_lshl_add_u32 v181, v181, 2, s14
	v_lshl_add_u32 v182, v182, 2, s14
	v_lshl_add_u32 v183, v183, 2, s14
	v_lshl_add_u32 v184, v184, 2, s14
	v_lshl_add_u32 v185, v185, 2, s14
	ds_read_b32 v178, v178 offset:384
	ds_read_b32 v179, v179 offset:380
	ds_read_b32 v180, v180 offset:376
	ds_read_b32 v181, v181 offset:372
	ds_read_b32 v182, v182 offset:320
	ds_read_b32 v183, v183 offset:316
	ds_read_b32 v184, v184 offset:312
	ds_read_b32 v185, v185 offset:308
	s_waitcnt lgkmcnt(9)
	v_fmac_f32_e32 v176, 0x3e0293ee, v160
	s_waitcnt lgkmcnt(8)
	v_fmac_f32_e32 v177, 0x3e0293ee, v161
	v_fmac_f32_e32 v170, 0x3e0293ee, v154
	v_fmac_f32_e32 v171, 0x3e0293ee, v155
	v_fmac_f32_e32 v172, 0x3e0293ee, v156
	v_fmac_f32_e32 v173, 0x3e0293ee, v157
	v_fmac_f32_e32 v174, 0x3e0293ee, v158
	v_fmac_f32_e32 v175, 0x3e0293ee, v159
	v_max_f32_e32 v234, v176, v177
	s_waitcnt lgkmcnt(5)
	v_fmac_f32_e32 v180, 0x3e0293ee, v164
	s_waitcnt lgkmcnt(4)
	v_fmac_f32_e32 v181, 0x3e0293ee, v165
	s_waitcnt lgkmcnt(1)
	v_fmac_f32_e32 v184, 0x3e0293ee, v168
	s_waitcnt lgkmcnt(0)
	v_fmac_f32_e32 v185, 0x3e0293ee, v169
	v_max_f32_e32 v197, v170, v171
	v_max_f32_e32 v201, v172, v173
	v_max3_f32 v234, v174, v175, v234
	v_fmac_f32_e32 v178, 0x3e0293ee, v162
	v_fmac_f32_e32 v179, 0x3e0293ee, v163
	v_fmac_f32_e32 v182, 0x3e0293ee, v166
	v_fmac_f32_e32 v183, 0x3e0293ee, v167
	v_max3_f32 v197, v197, v201, v234
	v_max_f32_e32 v201, v180, v181
	v_max_f32_e32 v234, v184, v185
	v_max3_f32 v201, v178, v179, v201
	v_max3_f32 v234, v182, v183, v234
	v_max3_f32 v197, v197, v201, v234
	v_mov_b32_e32 v201, v197
	s_nop 1
	v_permlane16_swap_b32_e32 v201, v197
	v_max_f32_e32 v197, v197, v201
	v_mov_b32_e32 v201, v197
	s_nop 1
	v_permlane32_swap_b32_e32 v201, v197
	v_max3_f32 v197, v233, v197, v201
	v_sub_f32_e32 v170, v170, v197
	v_sub_f32_e32 v171, v171, v197
	v_sub_f32_e32 v172, v172, v197
	v_sub_f32_e32 v173, v173, v197
	v_sub_f32_e32 v174, v174, v197
	v_sub_f32_e32 v175, v175, v197
	v_sub_f32_e32 v176, v176, v197
	v_sub_f32_e32 v177, v177, v197
	v_sub_f32_e32 v178, v178, v197
	v_sub_f32_e32 v179, v179, v197
	v_sub_f32_e32 v180, v180, v197
	v_sub_f32_e32 v181, v181, v197
	v_sub_f32_e32 v182, v182, v197
	v_sub_f32_e32 v183, v183, v197
	v_sub_f32_e32 v184, v184, v197
	v_exp_f32_e32 v170, v170
	v_exp_f32_e32 v171, v171
	v_exp_f32_e32 v172, v172
	v_exp_f32_e32 v173, v173
	v_exp_f32_e32 v174, v174
	v_exp_f32_e32 v175, v175
	v_exp_f32_e32 v176, v176
	v_exp_f32_e32 v177, v177
	v_exp_f32_e32 v178, v178
	v_exp_f32_e32 v179, v179
	v_exp_f32_e32 v180, v180
	v_exp_f32_e32 v181, v181
	v_exp_f32_e32 v182, v182
	v_exp_f32_e32 v183, v183
	v_exp_f32_e32 v184, v184
	v_sub_f32_e32 v201, v185, v197
	s_cbranch_execnz .LBB0_385
.LBB0_397:
	v_max_f32_e32 v170, v155, v155
	v_max_f32_e32 v171, v154, v154
	v_max_f32_e32 v170, v171, v170
	v_max_f32_e32 v171, v157, v157
	v_max_f32_e32 v172, v156, v156
	v_max_f32_e32 v171, v172, v171
	v_max_f32_e32 v172, v161, v161
	v_max_f32_e32 v173, v160, v160
	v_max_f32_e32 v172, v173, v172
	v_max3_f32 v172, v158, v159, v172
	v_max3_f32 v170, v170, v171, v172
	v_max_f32_e32 v171, v165, v165
	v_max_f32_e32 v172, v164, v164
	v_max_f32_e32 v171, v172, v171
	v_max_f32_e32 v172, v169, v169
	v_max_f32_e32 v173, v168, v168
	v_max_f32_e32 v172, v173, v172
	v_max3_f32 v171, v162, v163, v171
	v_max3_f32 v172, v166, v167, v172
	v_max3_f32 v170, v170, v171, v172
	v_mov_b32_e32 v172, s14
	ds_read_b32 v172, v172 offset:1024
	v_mov_b32_e32 v171, v170
	s_nop 1
	v_permlane16_swap_b32_e32 v171, v170
	v_max_f32_e32 v170, v170, v171
	v_mov_b32_e32 v171, v170
	s_nop 1
	v_permlane32_swap_b32_e32 v171, v170
	s_waitcnt lgkmcnt(0)
	v_max_f32_e32 v170, v170, v171
	v_fmamk_f32 v170, v170, 0x3e0293ee, v172
	v_max_f32_e32 v171, v233, v233
	v_max_f32_e32 v197, v171, v170
	v_sub_f32_e32 v201, v172, v197
	v_fmamk_f32 v154, v154, 0x3e0293ee, v201
	v_exp_f32_e32 v170, v154
	v_fmamk_f32 v154, v155, 0x3e0293ee, v201
	v_exp_f32_e32 v171, v154
	v_fmamk_f32 v154, v156, 0x3e0293ee, v201
	v_exp_f32_e32 v172, v154
	v_fmamk_f32 v154, v157, 0x3e0293ee, v201
	v_exp_f32_e32 v173, v154
	v_fmamk_f32 v154, v158, 0x3e0293ee, v201
	v_exp_f32_e32 v174, v154
	v_fmamk_f32 v154, v159, 0x3e0293ee, v201
	v_exp_f32_e32 v175, v154
	v_fmamk_f32 v154, v160, 0x3e0293ee, v201
	v_exp_f32_e32 v176, v154
	v_fmamk_f32 v154, v161, 0x3e0293ee, v201
	v_exp_f32_e32 v177, v154
	v_fmamk_f32 v154, v162, 0x3e0293ee, v201
	v_exp_f32_e32 v178, v154
	v_fmamk_f32 v154, v163, 0x3e0293ee, v201
	v_exp_f32_e32 v179, v154
	v_fmamk_f32 v154, v164, 0x3e0293ee, v201
	v_exp_f32_e32 v180, v154
	v_fmamk_f32 v154, v165, 0x3e0293ee, v201
	v_exp_f32_e32 v181, v154
	v_fmamk_f32 v154, v166, 0x3e0293ee, v201
	v_exp_f32_e32 v182, v154
	v_fmamk_f32 v154, v167, 0x3e0293ee, v201
	v_exp_f32_e32 v183, v154
	v_fmamk_f32 v154, v168, 0x3e0293ee, v201
	v_exp_f32_e32 v184, v154
	v_fmac_f32_e32 v201, 0x3e0293ee, v169
	v_sub_f32_e32 v154, v233, v197
	v_exp_f32_e32 v154, v154
	s_nop 0
	v_cmp_neq_f32_e32 vcc, 1.0, v154
	s_cbranch_vccnz .LBB0_386
	s_branch .LBB0_387
.LBB0_398:
	v_add_u32_e32 v162, 17, v227
	v_add_u32_e32 v164, 16, v227
	v_min_i32_e32 v163, 0x80, v162
	v_min_i32_e32 v164, 0x80, v164
	v_min_i32_e32 v165, 0x82, v162
	v_min_i32_e32 v166, 0x83, v162
	v_min_i32_e32 v168, 0x91, v162
	v_min_i32_e32 v169, 0x92, v162
	v_min_i32_e32 v170, 0x93, v162
	v_lshl_add_u32 v163, v163, 2, s14
	v_lshl_add_u32 v164, v164, 2, s14
	v_lshl_add_u32 v165, v165, 2, s14
	v_lshl_add_u32 v166, v166, 2, s14
	v_lshl_add_u32 v167, v199, 2, s14
	v_lshl_add_u32 v168, v168, 2, s14
	v_lshl_add_u32 v169, v169, 2, s14
	v_lshl_add_u32 v170, v170, 2, s14
	ds_read_b32 v163, v163 offset:512
	ds_read_b32 v164, v164 offset:512
	ds_read_b32 v165, v165 offset:504
	ds_read_b32 v166, v166 offset:500
	ds_read_b32 v167, v167 offset:512
	ds_read_b32 v168, v168 offset:444
	ds_read_b32 v169, v169 offset:440
	ds_read_b32 v173, v170 offset:436
	v_min_i32_e32 v170, 0xa0, v162
	v_min_i32_e32 v174, 0xa3, v162
	v_min_i32_e32 v175, 0xb0, v162
	v_min_i32_e32 v176, 0xb1, v162
	v_min_i32_e32 v177, 0xb2, v162
	v_lshl_add_u32 v170, v170, 2, s14
	v_min_i32_e32 v171, 0xa1, v162
	v_min_i32_e32 v172, 0xa2, v162
	v_lshl_add_u32 v174, v174, 2, s14
	v_lshl_add_u32 v175, v175, 2, s14
	v_lshl_add_u32 v176, v176, 2, s14
	v_lshl_add_u32 v177, v177, 2, s14
	v_min_i32_e32 v162, 0xb3, v162
	v_lshl_add_u32 v171, v171, 2, s14
	v_lshl_add_u32 v172, v172, 2, s14
	v_lshl_add_u32 v162, v162, 2, s14
	ds_read_b32 v179, v170 offset:384
	ds_read_b32 v180, v171 offset:380
	ds_read_b32 v181, v172 offset:376
	ds_read_b32 v174, v174 offset:372
	ds_read_b32 v175, v175 offset:320
	ds_read_b32 v176, v176 offset:316
	ds_read_b32 v177, v177 offset:312
	ds_read_b32 v182, v162 offset:308
	s_waitcnt lgkmcnt(9)
	v_fmac_f32_e32 v169, 0x3e0293ee, v144
	s_waitcnt lgkmcnt(8)
	v_fmac_f32_e32 v173, 0x3e0293ee, v145
	v_fmac_f32_e32 v163, 0x3e0293ee, v138
	v_fmac_f32_e32 v164, 0x3e0293ee, v139
	v_fmac_f32_e32 v165, 0x3e0293ee, v140
	v_fmac_f32_e32 v166, 0x3e0293ee, v141
	v_fmac_f32_e32 v167, 0x3e0293ee, v142
	v_fmac_f32_e32 v168, 0x3e0293ee, v143
	v_max_f32_e32 v171, v169, v173
	s_waitcnt lgkmcnt(5)
	v_fmac_f32_e32 v181, 0x3e0293ee, v148
	s_waitcnt lgkmcnt(4)
	v_fmac_f32_e32 v174, 0x3e0293ee, v149
	s_waitcnt lgkmcnt(1)
	v_fmac_f32_e32 v177, 0x3e0293ee, v152
	s_waitcnt lgkmcnt(0)
	v_fmac_f32_e32 v182, 0x3e0293ee, v153
	v_max_f32_e32 v162, v163, v164
	v_max_f32_e32 v170, v165, v166
	v_max3_f32 v171, v167, v168, v171
	v_fmac_f32_e32 v179, 0x3e0293ee, v146
	v_fmac_f32_e32 v180, 0x3e0293ee, v147
	v_fmac_f32_e32 v175, 0x3e0293ee, v150
	v_fmac_f32_e32 v176, 0x3e0293ee, v151
	v_max3_f32 v162, v162, v170, v171
	v_max_f32_e32 v170, v181, v174
	v_max_f32_e32 v171, v177, v182
	v_max3_f32 v170, v179, v180, v170
	v_max3_f32 v171, v175, v176, v171
	v_max3_f32 v162, v162, v170, v171
	v_mov_b32_e32 v170, v162
	s_nop 1
	v_permlane16_swap_b32_e32 v170, v162
	v_max_f32_e32 v162, v162, v170
	v_mov_b32_e32 v170, v162
	s_nop 1
	v_permlane32_swap_b32_e32 v170, v162
	v_max3_f32 v178, v232, v162, v170
	v_sub_f32_e32 v162, v163, v178
	v_sub_f32_e32 v163, v164, v178
	v_sub_f32_e32 v164, v165, v178
	v_sub_f32_e32 v165, v166, v178
	v_sub_f32_e32 v166, v167, v178
	v_exp_f32_e32 v170, v166
	v_sub_f32_e32 v166, v168, v178
	v_exp_f32_e32 v171, v166
	v_sub_f32_e32 v166, v169, v178
	v_exp_f32_e32 v172, v166
	v_sub_f32_e32 v166, v173, v178
	v_exp_f32_e32 v173, v166
	v_sub_f32_e32 v166, v179, v178
	v_sub_f32_e32 v167, v180, v178
	v_sub_f32_e32 v168, v181, v178
	v_sub_f32_e32 v169, v174, v178
	v_sub_f32_e32 v174, v175, v178
	v_sub_f32_e32 v175, v176, v178
	v_sub_f32_e32 v176, v177, v178
	v_exp_f32_e32 v162, v162
	v_exp_f32_e32 v163, v163
	v_exp_f32_e32 v164, v164
	v_exp_f32_e32 v165, v165
	v_exp_f32_e32 v166, v166
	v_exp_f32_e32 v167, v167
	v_exp_f32_e32 v168, v168
	v_exp_f32_e32 v169, v169
	v_exp_f32_e32 v174, v174
	v_exp_f32_e32 v175, v175
	v_exp_f32_e32 v176, v176
	v_sub_f32_e32 v179, v182, v178
	s_cbranch_execnz .LBB0_389
.LBB0_399:
	v_max_f32_e32 v162, v139, v139
	v_max_f32_e32 v163, v138, v138
	v_max_f32_e32 v162, v163, v162
	v_max_f32_e32 v163, v141, v141
	v_max_f32_e32 v164, v140, v140
	v_max_f32_e32 v163, v164, v163
	v_max_f32_e32 v164, v145, v145
	v_max_f32_e32 v165, v144, v144
	v_max_f32_e32 v164, v165, v164
	v_max3_f32 v164, v142, v143, v164
	v_max3_f32 v162, v162, v163, v164
	v_max_f32_e32 v163, v149, v149
	v_max_f32_e32 v164, v148, v148
	v_max_f32_e32 v163, v164, v163
	v_max_f32_e32 v164, v153, v153
	v_max_f32_e32 v165, v152, v152
	v_max_f32_e32 v164, v165, v164
	v_max3_f32 v163, v146, v147, v163
	v_max3_f32 v164, v150, v151, v164
	v_max3_f32 v162, v162, v163, v164
	v_mov_b32_e32 v164, s14
	ds_read_b32 v164, v164 offset:1024
	v_mov_b32_e32 v163, v162
	s_nop 1
	v_permlane16_swap_b32_e32 v163, v162
	v_max_f32_e32 v162, v162, v163
	v_mov_b32_e32 v163, v162
	s_nop 1
	v_permlane32_swap_b32_e32 v163, v162
	s_waitcnt lgkmcnt(0)
	v_max_f32_e32 v162, v162, v163
	v_fmamk_f32 v162, v162, 0x3e0293ee, v164
	v_max_f32_e32 v163, v232, v232
	v_max_f32_e32 v178, v163, v162
	v_sub_f32_e32 v179, v164, v178
	v_fmamk_f32 v138, v138, 0x3e0293ee, v179
	v_exp_f32_e32 v162, v138
	v_fmamk_f32 v138, v139, 0x3e0293ee, v179
	v_exp_f32_e32 v163, v138
	v_fmamk_f32 v138, v140, 0x3e0293ee, v179
	v_exp_f32_e32 v164, v138
	v_fmamk_f32 v138, v141, 0x3e0293ee, v179
	v_exp_f32_e32 v165, v138
	v_fmamk_f32 v138, v142, 0x3e0293ee, v179
	v_exp_f32_e32 v170, v138
	v_fmamk_f32 v138, v143, 0x3e0293ee, v179
	v_exp_f32_e32 v171, v138
	v_fmamk_f32 v138, v144, 0x3e0293ee, v179
	v_exp_f32_e32 v172, v138
	v_fmamk_f32 v138, v145, 0x3e0293ee, v179
	v_exp_f32_e32 v173, v138
	v_fmamk_f32 v138, v146, 0x3e0293ee, v179
	v_exp_f32_e32 v166, v138
	v_fmamk_f32 v138, v147, 0x3e0293ee, v179
	v_exp_f32_e32 v167, v138
	v_fmamk_f32 v138, v148, 0x3e0293ee, v179
	v_exp_f32_e32 v168, v138
	v_fmamk_f32 v138, v149, 0x3e0293ee, v179
	v_exp_f32_e32 v169, v138
	v_fmamk_f32 v138, v150, 0x3e0293ee, v179
	v_exp_f32_e32 v174, v138
	v_fmamk_f32 v138, v151, 0x3e0293ee, v179
	v_exp_f32_e32 v175, v138
	v_fmamk_f32 v138, v152, 0x3e0293ee, v179
	v_exp_f32_e32 v176, v138
	v_fmac_f32_e32 v179, 0x3e0293ee, v153
	v_sub_f32_e32 v138, v232, v178
	v_exp_f32_e32 v138, v138
	s_nop 0
	v_cmp_neq_f32_e32 vcc, 1.0, v138
	s_cbranch_vccnz .LBB0_390
	s_branch .LBB0_391

.LBB0_402:
	v_sub_f32_e32 v17, v17, v15
	v_sub_f32_e32 v16, v16, v15
	v_exp_f32_e32 v68, v17
	v_exp_f32_e32 v17, v16
	v_sub_f32_e32 v16, v27, v15
	v_exp_f32_e32 v153, v16
	v_sub_f32_e32 v16, v26, v15
	v_exp_f32_e32 v151, v16
	v_sub_f32_e32 v16, v25, v15
	v_exp_f32_e32 v149, v16
	v_sub_f32_e32 v16, v24, v15
	v_exp_f32_e32 v147, v16
	v_sub_f32_e32 v16, v23, v15
	v_exp_f32_e32 v145, v16
	v_sub_f32_e32 v16, v22, v15
	v_sub_f32_e32 v7, v7, v15
	v_exp_f32_e32 v143, v16
	v_exp_f32_e32 v155, v7
	v_sub_f32_e32 v7, v19, v15
	v_exp_f32_e32 v135, v7
	v_sub_f32_e32 v7, v18, v15
	v_exp_f32_e32 v133, v7
	v_sub_f32_e32 v7, v9, v15
	v_sub_f32_e32 v16, v21, v15
	v_exp_f32_e32 v131, v7
	v_sub_f32_e32 v7, v8, v15
	v_exp_f32_e32 v141, v16
	v_sub_f32_e32 v16, v20, v15
	v_exp_f32_e32 v129, v7
	v_cvt_pk_bf16_f32 v34, v143, v145
	v_cvt_pk_bf16_f32 v35, v147, v149
	v_cvt_pk_bf16_f32 v36, v151, v153
	v_cvt_pk_bf16_f32 v37, v17, v68
	v_mov_b32_e32 v7, v1
	v_exp_f32_e32 v139, v16
	v_sub_f32_e32 v6, v6, v15
	v_add_u32_e32 v16, v93, v7
	v_add_u32_e32 v69, 0xd000, v16
	ds_read2_b64 v[18:21], v69 offset1:4
	v_exp_f32_e32 v137, v6
	ds_read2_b64 v[6:9], v69 offset0:8 offset1:12
	v_cvt_pk_bf16_f32 v62, v129, v131
	v_cvt_pk_bf16_f32 v63, v133, v135
	v_cvt_pk_bf16_f32 v64, v137, v155
	v_cvt_pk_bf16_f32 v65, v139, v141
	v_add_u32_e32 v15, 0xd800, v16
	v_add_f32_e32 v0, 0, v0
	s_waitcnt lgkmcnt(1)
	v_mfma_f32_16x16x32_bf16 v[2:5], v[18:21], v[62:65], v[2:5]
	ds_read2_b64 v[18:21], v15 offset0:32 offset1:36
	v_add_f32_e32 v0, v156, v0
	s_add_u32 s18, s40, s47
	s_waitcnt lgkmcnt(1)
	v_mfma_f32_16x16x32_bf16 v[30:33], v[6:9], v[34:37], v[2:5]
	v_mad_i64_i32 v[66:67], s[14:15], v90, s59, 0
	s_addc_u32 s19, s41, 0
	s_nop 0
	ds_read2_b64 v[2:5], v15 offset0:40 offset1:44
	v_add_u32_e32 v15, 0xe000, v16
	s_waitcnt lgkmcnt(1)
	v_mfma_f32_16x16x32_bf16 v[6:9], v[18:21], v[62:65], v[58:61]
	ds_read2_b64 v[18:21], v15 offset0:64 offset1:68
	v_mov_b32_e32 v93, v1
	v_readlane_b32 s6, v236, 9
	s_waitcnt lgkmcnt(1)
	v_mfma_f32_16x16x32_bf16 v[26:29], v[2:5], v[34:37], v[6:9]
	ds_read2_b64 v[2:5], v15 offset0:72 offset1:76
	v_add_u32_e32 v15, 0xe800, v16
	v_readlane_b32 s7, v236, 10
	s_waitcnt lgkmcnt(1)
	v_mfma_f32_16x16x32_bf16 v[6:9], v[18:21], v[62:65], v[54:57]
	ds_read2_b64 v[18:21], v15 offset0:96 offset1:100
	s_waitcnt lgkmcnt(1)
	v_mfma_f32_16x16x32_bf16 v[22:25], v[2:5], v[34:37], v[6:9]
	ds_read2_b64 v[2:5], v15 offset0:104 offset1:108
	v_add_u32_e32 v15, 0xf000, v16
	s_waitcnt lgkmcnt(1)
	v_mfma_f32_16x16x32_bf16 v[6:9], v[18:21], v[62:65], v[50:53]
	s_nop 2
	ds_read2_b64 v[50:53], v15 offset0:128 offset1:132
	s_waitcnt lgkmcnt(1)
	v_mfma_f32_16x16x32_bf16 v[18:21], v[2:5], v[34:37], v[6:9]
	ds_read2_b64 v[2:5], v15 offset0:136 offset1:140
	v_add_u32_e32 v15, 0xf800, v16
	s_waitcnt lgkmcnt(1)
	v_mfma_f32_16x16x32_bf16 v[6:9], v[50:53], v[62:65], v[46:49]
	s_nop 2
	ds_read2_b64 v[46:49], v15 offset0:160 offset1:164
	ds_read2_b64 v[50:53], v15 offset0:168 offset1:172
	v_add_u32_e32 v15, 0x3000, v69
	s_waitcnt lgkmcnt(2)
	v_mfma_f32_16x16x32_bf16 v[6:9], v[2:5], v[34:37], v[6:9]
	s_waitcnt lgkmcnt(1)
	v_mfma_f32_16x16x32_bf16 v[2:5], v[46:49], v[62:65], v[42:45]
	ds_read2_b64 v[46:49], v15 offset0:192 offset1:196
	ds_read2_b64 v[54:57], v15 offset0:200 offset1:204
	v_add_u32_e32 v15, 0x3800, v69
	v_lshl_add_u64 v[42:43], s[18:19], 0, v[66:67]
	s_waitcnt lgkmcnt(1)
	v_mfma_f32_16x16x32_bf16 v[38:41], v[46:49], v[62:65], v[38:41]
	v_add_f32_e64 v46, v110, v0
	v_add_f32_e64 v47, v111, v1
	v_lshl_add_u64 v[42:43], v[42:43], 0, v[92:93]
	v_pk_add_f32 v[46:47], v[112:113], v[46:47]
	v_mfma_f32_16x16x32_bf16 v[2:5], v[50:53], v[34:37], v[2:5]
	v_add_f32_e64 v46, v114, v46
	v_add_f32_e64 v47, v115, v47
	ds_read2_b64 v[50:53], v15 offset0:224 offset1:228
	ds_read2_b64 v[58:61], v15 offset0:232 offset1:236
	v_pk_add_f32 v[46:47], v[116:117], v[46:47]
	s_waitcnt lgkmcnt(0)
	s_barrier
	global_load_dwordx2 v[44:45], v[42:43], off nt
	v_pk_add_f32 v[46:47], v[118:119], v[46:47]
	v_mfma_f32_16x16x32_bf16 v[10:13], v[50:53], v[62:65], v[10:13]
	v_add_f32_e64 v46, v122, v46
	v_add_f32_e64 v47, v123, v47
	s_add_u32 s18, s42, s47
	v_pk_add_f32 v[46:47], v[94:95], v[46:47]
	v_mfma_f32_16x16x32_bf16 v[10:13], v[58:61], v[34:37], v[10:13]
	v_add_f32_e64 v46, v96, v46
	v_add_f32_e64 v47, v97, v47
	s_addc_u32 s19, s43, 0
	v_pk_add_f32 v[46:47], v[98:99], v[46:47]
	s_add_i32 s46, s46, s6
	v_pk_add_f32 v[46:47], v[100:101], v[46:47]
	s_add_i32 s45, s45, s35
	v_pk_add_f32 v[46:47], v[102:103], v[46:47]
	s_add_i32 s44, s44, s30
	v_pk_add_f32 v[46:47], v[104:105], v[46:47]
	s_cmpk_gt_i32 s46, 0xff
	v_pk_add_f32 v[46:47], v[106:107], v[46:47]
	s_waitcnt vmcnt(0)
	v_lshlrev_b32_e32 v49, 16, v44
	v_pk_add_f32 v[46:47], v[108:109], v[46:47]
	v_and_b32_e32 v44, 0xffff0000, v44
	v_pk_add_f32 v[46:47], v[120:121], v[46:47]
	s_nop 0
	v_add_f32_e32 v0, v47, v157
	v_fmac_f32_e32 v0, v46, v124
	v_mul_f32_e32 v16, v0, v126
	v_add_f32_e32 v0, 0, v127
	v_add_f32_e32 v0, v158, v0
	v_pk_add_f32 v[46:47], v[128:129], v[0:1]
	s_nop 0
	v_pk_add_f32 v[46:47], v[130:131], v[46:47]
	s_nop 0
	v_pk_add_f32 v[46:47], v[132:133], v[46:47]
	s_nop 0
	v_pk_add_f32 v[46:47], v[134:135], v[46:47]
	s_nop 0
	v_pk_add_f32 v[46:47], v[136:137], v[46:47]
	s_nop 0
	v_pk_add_f32 v[46:47], v[154:155], v[46:47]
	s_nop 0
	v_pk_add_f32 v[46:47], v[138:139], v[46:47]
	s_nop 0
	v_pk_add_f32 v[46:47], v[140:141], v[46:47]
	s_nop 0
	v_pk_add_f32 v[46:47], v[142:143], v[46:47]
	s_nop 0
	v_pk_add_f32 v[46:47], v[144:145], v[46:47]
	s_nop 0
	v_pk_add_f32 v[46:47], v[146:147], v[46:47]
	s_nop 0
	v_pk_add_f32 v[46:47], v[148:149], v[46:47]
	s_nop 0
	v_pk_add_f32 v[46:47], v[150:151], v[46:47]
	s_nop 0
	v_pk_add_f32 v[46:47], v[152:153], v[46:47]
	s_nop 0
	v_pk_add_f32 v[16:17], v[16:17], v[46:47]
	s_nop 0
	v_add_f32_e32 v0, v17, v68
	v_fmac_f32_e32 v0, v16, v14
	ds_bpermute_b32 v46, v91, v0
	v_mfma_f32_16x16x32_bf16 v[14:17], v[54:57], v[34:37], v[38:41]
	v_and_b32_e32 v54, 0xffff0000, v45
	v_ashrrev_i32_e32 v91, 31, v90
	s_waitcnt lgkmcnt(0)
	v_add_f32_e32 v0, v0, v46
	ds_bpermute_b32 v38, v125, v0
	v_mul_f32_e32 v40, 0xbfb8aa3b, v49
	v_mul_f32_e32 v41, 0xbfb8aa3b, v44
	v_exp_f32_e32 v40, v40
	v_exp_f32_e32 v41, v41
	s_waitcnt lgkmcnt(0)
	v_add_f32_e32 v0, v0, v38
	v_div_scale_f32 v38, s[14:15], v0, v0, 1.0
	v_rcp_f32_e32 v46, v38
	v_pk_add_f32 v[40:41], v[40:41], 1.0 op_sel_hi:[1,0]
	v_fma_f32 v34, -v38, v46, 1.0
	v_fmac_f32_e32 v46, v34, v46
	v_div_scale_f32 v34, vcc, 1.0, v0, 1.0
	v_mul_f32_e32 v47, v34, v46
	v_fma_f32 v35, -v38, v47, v34
	v_fmac_f32_e32 v47, v35, v46
	v_fma_f32 v48, -v38, v47, v34
	global_load_dwordx2 v[36:37], v[42:43], off offset:32 nt
	global_load_dwordx2 v[38:39], v[42:43], off offset:64 nt
	global_load_dwordx2 v[34:35], v[42:43], off offset:96 nt
	v_div_fmas_f32 v46, v48, v46, v47
	v_div_scale_f32 v48, s[14:15], v41, v41, v44
	v_rcp_f32_e32 v50, v48
	v_div_fixup_f32 v0, v46, v0, 1.0
	v_pk_mul_f32 v[30:31], v[30:31], v[0:1] op_sel_hi:[1,0]
	v_pk_mul_f32 v[32:33], v[32:33], v[0:1] op_sel_hi:[1,0]
	v_fma_f32 v51, -v48, v50, 1.0
	v_fmac_f32_e32 v50, v51, v50
	v_div_scale_f32 v51, vcc, v44, v41, v44
	v_mul_f32_e32 v52, v51, v50
	v_fma_f32 v53, -v48, v52, v51
	v_fmac_f32_e32 v52, v53, v50
	v_fma_f32 v48, -v48, v52, v51
	v_div_fmas_f32 v48, v48, v50, v52
	v_div_fixup_f32 v41, v48, v41, v44
	v_lshlrev_b32_e32 v52, 16, v45
	v_mul_f32_e32 v44, 0xbfb8aa3b, v52
	v_mul_f32_e32 v45, 0xbfb8aa3b, v54
	v_exp_f32_e32 v44, v44
	v_exp_f32_e32 v45, v45
	v_rcp_f32_e32 v48, v40
	s_nop 0
	v_mul_f32_e32 v40, v49, v48
	v_pk_add_f32 v[44:45], v[44:45], 1.0 op_sel_hi:[1,0]
	v_pk_mul_f32 v[30:31], v[30:31], v[40:41]
	v_lshlrev_b64 v[46:47], 12, v[90:91]
	v_lshl_add_u64 v[46:47], s[18:19], 0, v[46:47]
	v_pk_mul_f32 v[26:27], v[26:27], v[0:1] op_sel_hi:[1,0]
	v_rcp_f32_e32 v40, v45
	s_nop 0
	v_mul_f32_e32 v41, v54, v40
	v_rcp_f32_e32 v40, v44
	s_nop 0
	v_mul_f32_e32 v40, v52, v40
	v_pk_mul_f32 v[32:33], v[32:33], v[40:41]
	v_cvt_pk_bf16_f32 v40, v30, v31
	v_cvt_pk_bf16_f32 v41, v32, v33
	v_lshl_add_u64 v[30:31], v[46:47], 0, v[92:93]
	global_store_dwordx2 v[30:31], v[40:41], off
	v_pk_mul_f32 v[28:29], v[28:29], v[0:1] op_sel_hi:[1,0]
	v_pk_mul_f32 v[22:23], v[22:23], v[0:1] op_sel_hi:[1,0]
	v_pk_mul_f32 v[24:25], v[24:25], v[0:1] op_sel_hi:[1,0]
	v_pk_mul_f32 v[20:21], v[20:21], v[0:1] op_sel_hi:[1,0]
	v_pk_mul_f32 v[6:7], v[6:7], v[0:1] op_sel_hi:[1,0]
	v_pk_mul_f32 v[8:9], v[8:9], v[0:1] op_sel_hi:[1,0]
	s_waitcnt vmcnt(3)
	v_lshlrev_b32_e32 v48, 16, v36
	v_and_b32_e32 v36, 0xffff0000, v36
	v_mul_f32_e32 v44, 0xbfb8aa3b, v48
	v_mul_f32_e32 v45, 0xbfb8aa3b, v36
	v_exp_f32_e32 v44, v44
	v_exp_f32_e32 v45, v45
	v_and_b32_e32 v47, 0xffff0000, v37
	v_pk_mul_f32 v[2:3], v[2:3], v[0:1] op_sel_hi:[1,0]
	v_pk_mul_f32 v[4:5], v[4:5], v[0:1] op_sel_hi:[1,0]
	v_pk_add_f32 v[32:33], v[44:45], 1.0 op_sel_hi:[1,0]
	s_nop 0
	s_nop 0
	v_rcp_f32_e32 v40, v33
	s_nop 0
	v_mul_f32_e32 v33, v36, v40
	v_lshlrev_b32_e32 v45, 16, v37
	v_mul_f32_e32 v36, 0xbfb8aa3b, v45
	v_mul_f32_e32 v37, 0xbfb8aa3b, v47
	v_exp_f32_e32 v36, v36
	v_exp_f32_e32 v37, v37
	v_rcp_f32_e32 v40, v32
	s_nop 0
	v_mul_f32_e32 v32, v48, v40
	v_pk_add_f32 v[36:37], v[36:37], 1.0 op_sel_hi:[1,0]
	v_pk_mul_f32 v[26:27], v[26:27], v[32:33]
	v_cvt_pk_bf16_f32 v26, v26, v27
	v_rcp_f32_e32 v32, v37
	s_nop 0
	v_mul_f32_e32 v33, v47, v32
	s_waitcnt vmcnt(2)
	v_lshlrev_b32_e32 v37, 16, v38
	v_and_b32_e32 v38, 0xffff0000, v38
	v_mul_f32_e32 v40, 0xbfb8aa3b, v37
	v_mul_f32_e32 v41, 0xbfb8aa3b, v38
	v_exp_f32_e32 v40, v40
	v_exp_f32_e32 v41, v41
	v_rcp_f32_e32 v32, v36
	s_nop 0
	v_mul_f32_e32 v32, v45, v32
	v_pk_mul_f32 v[28:29], v[28:29], v[32:33]
	v_pk_add_f32 v[32:33], v[40:41], 1.0 op_sel_hi:[1,0]
	s_nop 0
	v_cvt_pk_bf16_f32 v27, v28, v29
	global_store_dwordx2 v[30:31], v[26:27], off offset:32
	v_rcp_f32_e32 v26, v33
	s_nop 0
	v_mul_f32_e32 v27, v38, v26
	v_lshlrev_b32_e32 v38, 16, v39
	v_and_b32_e32 v39, 0xffff0000, v39
	v_mul_f32_e32 v28, 0xbfb8aa3b, v38
	v_mul_f32_e32 v29, 0xbfb8aa3b, v39
	v_exp_f32_e32 v28, v28
	v_exp_f32_e32 v29, v29
	v_rcp_f32_e32 v26, v32
	s_nop 0
	v_mul_f32_e32 v26, v37, v26
	v_pk_add_f32 v[28:29], v[28:29], 1.0 op_sel_hi:[1,0]
	v_pk_mul_f32 v[26:27], v[22:23], v[26:27]
	s_waitcnt vmcnt(2)
	v_lshlrev_b32_e32 v37, 16, v34
	v_and_b32_e32 v34, 0xffff0000, v34
	v_cvt_pk_bf16_f32 v26, v26, v27
	v_rcp_f32_e32 v22, v29
	s_nop 0
	v_mul_f32_e32 v29, v39, v22
	global_load_dwordx2 v[22:23], v[42:43], off offset:128 nt
	v_mul_f32_e32 v32, 0xbfb8aa3b, v37
	v_mul_f32_e32 v33, 0xbfb8aa3b, v34
	v_exp_f32_e32 v32, v32
	v_exp_f32_e32 v33, v33
	v_rcp_f32_e32 v36, v28
	s_nop 0
	v_mul_f32_e32 v28, v38, v36
	v_pk_mul_f32 v[24:25], v[24:25], v[28:29]
	v_lshlrev_b32_e32 v36, 16, v35
	v_pk_add_f32 v[28:29], v[32:33], 1.0 op_sel_hi:[1,0]
	v_cvt_pk_bf16_f32 v27, v24, v25
	v_pk_mul_f32 v[24:25], v[18:19], v[0:1] op_sel_hi:[1,0]
	global_store_dwordx2 v[30:31], v[26:27], off offset:64
	v_rcp_f32_e32 v18, v29
	s_nop 0
	v_mul_f32_e32 v27, v34, v18
	v_and_b32_e32 v34, 0xffff0000, v35
	v_mul_f32_e32 v18, 0xbfb8aa3b, v36
	v_mul_f32_e32 v19, 0xbfb8aa3b, v34
	v_exp_f32_e32 v18, v18
	v_exp_f32_e32 v19, v19
	v_rcp_f32_e32 v26, v28
	s_nop 0
	v_mul_f32_e32 v26, v37, v26
	v_pk_add_f32 v[18:19], v[18:19], 1.0 op_sel_hi:[1,0]
	v_pk_mul_f32 v[24:25], v[24:25], v[26:27]
	s_waitcnt vmcnt(1)
	v_lshlrev_b32_e32 v38, 16, v22
	v_rcp_f32_e32 v26, v19
	s_nop 0
	v_mul_f32_e32 v19, v34, v26
	v_and_b32_e32 v22, 0xffff0000, v22
	global_load_dwordx2 v[26:27], v[42:43], off offset:160 nt
	global_load_dwordx2 v[28:29], v[42:43], off offset:192 nt
	global_load_dwordx2 v[32:33], v[42:43], off offset:224 nt
	v_mul_f32_e32 v34, 0xbfb8aa3b, v38
	v_mul_f32_e32 v35, 0xbfb8aa3b, v22
	v_exp_f32_e32 v34, v34
	v_exp_f32_e32 v35, v35
	v_rcp_f32_e32 v37, v18
	s_nop 0
	v_mul_f32_e32 v18, v36, v37
	v_pk_mul_f32 v[18:19], v[20:21], v[18:19]
	v_cvt_pk_bf16_f32 v20, v24, v25
	v_pk_add_f32 v[24:25], v[34:35], 1.0 op_sel_hi:[1,0]
	v_cvt_pk_bf16_f32 v21, v18, v19
	global_store_dwordx2 v[30:31], v[20:21], off offset:96
	v_rcp_f32_e32 v18, v25
	s_nop 0
	v_mul_f32_e32 v19, v22, v18
	v_lshlrev_b32_e32 v25, 16, v23
	v_and_b32_e32 v23, 0xffff0000, v23
	v_mul_f32_e32 v20, 0xbfb8aa3b, v25
	v_mul_f32_e32 v21, 0xbfb8aa3b, v23
	v_exp_f32_e32 v20, v20
	v_exp_f32_e32 v21, v21
	v_rcp_f32_e32 v18, v24
	s_nop 0
	v_mul_f32_e32 v18, v38, v18
	v_pk_add_f32 v[20:21], v[20:21], 1.0 op_sel_hi:[1,0]
	v_pk_mul_f32 v[6:7], v[6:7], v[18:19]
	v_cvt_pk_bf16_f32 v6, v6, v7
	v_rcp_f32_e32 v18, v21
	s_nop 0
	v_mul_f32_e32 v19, v23, v18
	v_rcp_f32_e32 v18, v20
	s_nop 0
	v_mul_f32_e32 v18, v25, v18
	v_pk_mul_f32 v[8:9], v[8:9], v[18:19]
	s_waitcnt vmcnt(3)
	v_lshlrev_b32_e32 v21, 16, v26
	v_and_b32_e32 v24, 0xffff0000, v26
	v_mul_f32_e32 v22, 0xbfb8aa3b, v21
	v_mul_f32_e32 v23, 0xbfb8aa3b, v24
	v_exp_f32_e32 v22, v22
	v_exp_f32_e32 v23, v23
	v_cvt_pk_bf16_f32 v7, v8, v9
	global_store_dwordx2 v[30:31], v[6:7], off offset:128
	v_pk_add_f32 v[18:19], v[22:23], 1.0 op_sel_hi:[1,0]
	s_nop 0
	s_nop 0
	v_rcp_f32_e32 v6, v19
	s_nop 0
	v_mul_f32_e32 v7, v24, v6
	v_lshlrev_b32_e32 v22, 16, v27
	v_and_b32_e32 v24, 0xffff0000, v27
	v_mul_f32_e32 v8, 0xbfb8aa3b, v22
	v_mul_f32_e32 v9, 0xbfb8aa3b, v24
	v_exp_f32_e32 v8, v8
	v_exp_f32_e32 v9, v9
	v_rcp_f32_e32 v6, v18
	s_nop 0
	v_mul_f32_e32 v6, v21, v6
	v_pk_add_f32 v[8:9], v[8:9], 1.0 op_sel_hi:[1,0]
	v_pk_mul_f32 v[2:3], v[2:3], v[6:7]
	v_cvt_pk_bf16_f32 v2, v2, v3
	v_rcp_f32_e32 v6, v9
	s_nop 0
	v_mul_f32_e32 v7, v24, v6
	s_waitcnt vmcnt(3)
	v_lshlrev_b32_e32 v20, 16, v28
	v_and_b32_e32 v9, 0xffff0000, v28
	v_mul_f32_e32 v18, 0xbfb8aa3b, v20
	v_mul_f32_e32 v19, 0xbfb8aa3b, v9
	v_exp_f32_e32 v18, v18
	v_exp_f32_e32 v19, v19
	v_rcp_f32_e32 v6, v8
	s_nop 0
	v_mul_f32_e32 v6, v22, v6
	v_pk_mul_f32 v[4:5], v[4:5], v[6:7]
	v_pk_add_f32 v[6:7], v[18:19], 1.0 op_sel_hi:[1,0]
	s_nop 0
	v_cvt_pk_bf16_f32 v3, v4, v5
	global_store_dwordx2 v[30:31], v[2:3], off offset:160
	v_pk_mul_f32 v[2:3], v[14:15], v[0:1] op_sel_hi:[1,0]
	v_rcp_f32_e32 v4, v7
	s_nop 0
	v_mul_f32_e32 v5, v9, v4
	v_lshlrev_b32_e32 v18, 16, v29
	v_and_b32_e32 v19, 0xffff0000, v29
	v_mul_f32_e32 v8, 0xbfb8aa3b, v18
	v_mul_f32_e32 v9, 0xbfb8aa3b, v19
	v_exp_f32_e32 v8, v8
	v_exp_f32_e32 v9, v9
	v_rcp_f32_e32 v4, v6
	s_nop 0
	v_mul_f32_e32 v4, v20, v4
	v_pk_add_f32 v[8:9], v[8:9], 1.0 op_sel_hi:[1,0]
	v_pk_mul_f32 v[2:3], v[2:3], v[4:5]
	v_pk_mul_f32 v[4:5], v[16:17], v[0:1] op_sel_hi:[1,0]
	v_cvt_pk_bf16_f32 v2, v2, v3
	v_rcp_f32_e32 v6, v9
	s_nop 0
	v_mul_f32_e32 v7, v19, v6
	s_waitcnt vmcnt(3)
	v_lshlrev_b32_e32 v16, 16, v32
	v_and_b32_e32 v9, 0xffff0000, v32
	v_mul_f32_e32 v14, 0xbfb8aa3b, v16
	v_mul_f32_e32 v15, 0xbfb8aa3b, v9
	v_exp_f32_e32 v14, v14
	v_exp_f32_e32 v15, v15
	v_rcp_f32_e32 v6, v8
	s_nop 0
	v_mul_f32_e32 v6, v18, v6
	v_pk_mul_f32 v[4:5], v[4:5], v[6:7]
	v_pk_add_f32 v[6:7], v[14:15], 1.0 op_sel_hi:[1,0]
	s_nop 0
	v_cvt_pk_bf16_f32 v3, v4, v5
	global_store_dwordx2 v[30:31], v[2:3], off offset:192
	v_pk_mul_f32 v[2:3], v[10:11], v[0:1] op_sel_hi:[1,0]
	v_rcp_f32_e32 v4, v7
	s_nop 0
	v_mul_f32_e32 v5, v9, v4
	v_lshlrev_b32_e32 v14, 16, v33
	v_and_b32_e32 v15, 0xffff0000, v33
	v_mul_f32_e32 v8, 0xbfb8aa3b, v14
	v_mul_f32_e32 v9, 0xbfb8aa3b, v15
	v_exp_f32_e32 v8, v8
	v_exp_f32_e32 v9, v9
	v_rcp_f32_e32 v4, v6
	s_nop 0
	v_mul_f32_e32 v4, v16, v4
	v_pk_add_f32 v[8:9], v[8:9], 1.0 op_sel_hi:[1,0]
	v_pk_mul_f32 v[2:3], v[2:3], v[4:5]
	v_pk_mul_f32 v[4:5], v[12:13], v[0:1] op_sel_hi:[1,0]
	v_cvt_pk_bf16_f32 v2, v2, v3
	v_rcp_f32_e32 v0, v9
	s_nop 0
	v_mul_f32_e32 v7, v15, v0
	v_rcp_f32_e32 v0, v8
	s_nop 0
	v_mul_f32_e32 v6, v14, v0
	v_pk_mul_f32 v[4:5], v[4:5], v[6:7]
	s_nop 0
	v_cvt_pk_bf16_f32 v3, v4, v5
	global_store_dwordx2 v[30:31], v[2:3], off offset:224
	s_cbranch_scc1 .LBB0_409

.LBB0_412:
	s_ashr_i32 s24, s42, 2
	s_and_b32 s25, s42, 3
	s_lshl_b32 s44, s24, 6
	s_mul_i32 s0, s24, 0xa8000
	s_mul_hi_i32 s1, s44, 0x2a00
	s_add_u32 s46, s4, s0
	s_addc_u32 s47, s5, s1
	s_ashr_i32 s45, s44, 31
	s_lshl_b32 s43, s25, 6
	v_mov_b32_e32 v20, v204
	v_mov_b32_e32 v4, v204
	v_lshlrev_b32_e32 v21, 2, v204
	v_mov_b32_e32 v0, s43
	v_readfirstlane_b32 s23, v204
	v_lshrrev_b32_e32 v113, 3, v204
	v_and_b32_e32 v114, 7, v204
	v_lshlrev_b32_e32 v114, 4, v114
	v_mad_u32_u24 v112, v113, s59, v114
	v_mul_u32_u24_e32 v115, 0x4080, v113
	v_add_u32_e32 v115, v115, v114
	v_lshrrev_b32_e32 v116, 1, v204
	v_and_b32_e32 v117, 1, v204
	v_lshlrev_b32_e32 v117, 4, v117
	v_mad_u32_u24 v116, v116, s59, v117
	v_lshrrev_b32_e32 v118, 6, v204
	v_and_b32_e32 v119, 63, v204
	v_lshlrev_b32_e32 v119, 2, v119
	v_lshl_add_u32 v118, v118, 10, v119
	s_add_u32 s48, s46, 0x2800
	s_addc_u32 s49, s47, 0
	v_cmp_gt_u32_e32 vcc, 0x80, v204
	s_and_saveexec_b64 s[0:1], vcc
	s_cbranch_execz .Lg1_lr_skip
	global_load_dwordx4 v[120:123], v116, s[48:49]
.Lg1_lr_skip:
	s_or_b64 exec, exec, s[0:1]
	s_lshl_b32 s31, s25, 8
	s_add_u32 s36, s38, s31
	s_addc_u32 s37, s39, 0
	s_add_u32 s6, s36, 0x2000
	s_addc_u32 s7, s37, 0
	global_load_dword v124, v118, s[36:37]
	global_load_dword v125, v118, s[6:7]
	s_add_u32 s48, s40, s31
	s_addc_u32 s49, s41, 0
	v_cmp_gt_u32_e32 vcc, 64, v204
	s_and_saveexec_b64 s[0:1], vcc
	s_cbranch_execz .Lg1_gb_skip
	global_load_dword v126, v21, s[48:49]
.Lg1_gb_skip:
	s_or_b64 exec, exec, s[0:1]
	s_lshl_b32 s31, s25, 7
	s_addk_i32 s31, 0x1a00
	s_add_u32 s36, s46, s31
	s_addc_u32 s37, s47, 0
	global_load_dwordx4 v[100:103], v112, s[36:37]
	s_lshl_b32 s31, s25, 7
	s_addk_i32 s31, 0x400
	s_mul_i32 s31, s31, 0x4080
	s_lshl_b32 s6, s24, 7
	s_add_i32 s31, s31, s6
	s_add_u32 s6, s8, s31
	s_addc_u32 s7, s9, 0
	global_load_dwordx4 v[104:107], v115, s[6:7]
	s_add_u32 s48, s6, 0x102000
	s_addc_u32 s49, s7, 0
	global_load_dwordx4 v[108:111], v115, s[48:49]
	s_waitcnt vmcnt(3)
	v_cmp_gt_u32_e32 vcc, 0x80, v204
	s_and_saveexec_b64 s[0:1], vcc
	s_cbranch_execz .Lg1_lr_done
	v_lshlrev_b32_e32 v127, 5, v204
	v_lshlrev_b32_e32 v10, 16, v120
	v_and_b32_e32 v11, 0xffff0000, v120
	v_lshlrev_b32_e32 v12, 16, v121
	v_and_b32_e32 v13, 0xffff0000, v121
	v_lshlrev_b32_e32 v6, 16, v122
	v_and_b32_e32 v7, 0xffff0000, v122
	v_lshlrev_b32_e32 v8, 16, v123
	v_and_b32_e32 v9, 0xffff0000, v123
	ds_write_b128 v127, v[10:13]
	ds_write_b128 v127, v[6:9] offset:16
.Lg1_lr_done:
	s_or_b64 exec, exec, s[0:1]
	v_add_u32_e32 v127, 0x1000, v21
	ds_write2st64_b32 v127, v124, v125 offset1:8
	v_cmp_gt_u32_e32 vcc, 64, v204
	s_and_saveexec_b64 s[0:1], vcc
	s_cbranch_execz .Lg1_gb_done
	ds_write_b32 v21, v126 offset:8192
.Lg1_gb_done:
	s_or_b64 exec, exec, s[0:1]
	v_and_b32_e32 v2, 63, v4
	v_lshl_add_u32 v2, v2, 2, 0
	s_waitcnt lgkmcnt(0)
	s_barrier
	ds_read2st64_b32 v[18:19], v2 offset0:16 offset1:17
	ds_read2st64_b32 v[16:17], v2 offset0:18 offset1:19
	ds_read2st64_b32 v[14:15], v2 offset0:20 offset1:21
	ds_read2st64_b32 v[12:13], v2 offset0:22 offset1:23
	ds_read_b32 v22, v2 offset:8192
	v_ashrrev_i32_e32 v3, 6, v4
	v_lshl_add_u32 v23, v3, 9, 0
	ds_read_b128 v[24:27], v23
	ds_read2st64_b32 v[10:11], v2 offset0:24 offset1:25
	ds_read2st64_b32 v[8:9], v2 offset0:26 offset1:27
	ds_read2st64_b32 v[6:7], v2 offset0:28 offset1:29
	ds_read2st64_b32 v[4:5], v2 offset0:30 offset1:31
	ds_read_b128 v[28:31], v23 offset:16
	ds_read_b128 v[32:35], v23 offset:32
	ds_read_b128 v[36:39], v23 offset:48
	s_mov_b32 s6, 0xbfb8aa3b
	s_waitcnt lgkmcnt(0)
	v_fma_f32 v24, v18, v24, v22
	v_fmac_f32_e32 v24, v19, v25
	v_fmac_f32_e32 v24, v16, v26
	v_fmac_f32_e32 v24, v17, v27
	v_fmac_f32_e32 v24, v14, v28
	v_fmac_f32_e32 v24, v15, v29
	v_fmac_f32_e32 v24, v12, v30
	v_fmac_f32_e32 v24, v13, v31
	v_fmac_f32_e32 v24, v10, v32
	v_fmac_f32_e32 v24, v11, v33
	v_fmac_f32_e32 v24, v8, v34
	v_fmac_f32_e32 v24, v9, v35
	v_fmac_f32_e32 v24, v6, v36
	v_fmac_f32_e32 v24, v7, v37
	v_fmac_f32_e32 v24, v4, v38
	v_fmac_f32_e32 v24, v5, v39
	v_mul_f32_e64 v25, |v24|, s6
	v_exp_f32_e32 v25, v25
	v_min_f32_e32 v33, 0, v24
	s_mov_b32 s7, 0x3f317217
	s_mov_b32 s31, 0x7f800000
	v_add_f32_e32 v25, 1.0, v25
	v_cmp_gt_f32_e32 vcc, s89, v25
	s_nop 1
	v_cndmask_b32_e64 v26, 0, 32, vcc
	v_ldexp_f32 v25, v25, v26
	v_log_f32_e32 v32, v25
	ds_read_b128 v[24:27], v23 offset:64
	v_mul_f32_e32 v28, 0x3f317217, v32
	v_fma_f32 v34, v32, s7, -v28
	ds_read_b128 v[28:31], v23 offset:80
	s_waitcnt lgkmcnt(0)
	v_fma_f32 v35, v18, v24, v22
	v_fmac_f32_e32 v35, v19, v25
	v_fmac_f32_e32 v35, v16, v26
	v_fmac_f32_e32 v35, v17, v27
	ds_read_b128 v[24:27], v23 offset:96
	v_fmac_f32_e32 v35, v14, v28
	v_fmac_f32_e32 v35, v15, v29
	v_fmac_f32_e32 v35, v12, v30
	v_fmac_f32_e32 v35, v13, v31
	ds_read_b128 v[28:31], v23 offset:112
	s_waitcnt lgkmcnt(0)
	v_fmac_f32_e32 v35, v10, v24
	v_fmac_f32_e32 v35, v11, v25
	v_fmac_f32_e32 v35, v8, v26
	v_fmac_f32_e32 v35, v9, v27
	v_fmac_f32_e32 v35, v6, v28
	v_fmac_f32_e32 v35, v7, v29
	v_fmac_f32_e32 v35, v4, v30
	v_fmac_f32_e32 v35, v5, v31
	v_mul_f32_e64 v24, |v35|, s6
	v_exp_f32_e32 v24, v24
	v_fmac_f32_e32 v34, 0x3377d1cf, v32
	v_fmac_f32_e32 v34, 0x3f317217, v32
	v_cmp_lt_f32_e64 s[0:1], |v32|, s31
	v_add_f32_e32 v24, 1.0, v24
	v_cndmask_b32_e32 v26, 0, v213, vcc
	v_cndmask_b32_e64 v25, v32, v34, s[0:1]
	v_cmp_gt_f32_e32 vcc, s89, v24
	v_sub_f32_e32 v25, v25, v26
	s_mov_b32 s0, 0x3d800000
	v_cndmask_b32_e64 v26, 0, 32, vcc
	v_ldexp_f32 v24, v24, v26
	v_log_f32_e32 v34, v24
	ds_read_b128 v[26:29], v23 offset:128
	v_sub_f32_e32 v24, v33, v25
	v_min_f32_e32 v25, 0, v35
	v_mul_f32_e32 v30, 0x3f317217, v34
	v_fma_f32 v35, v34, s7, -v30
	ds_read_b128 v[30:33], v23 offset:144
	s_waitcnt lgkmcnt(0)
	v_fma_f32 v36, v18, v26, v22
	v_fmac_f32_e32 v36, v19, v27
	v_fmac_f32_e32 v36, v16, v28
	v_fmac_f32_e32 v36, v17, v29
	ds_read_b128 v[26:29], v23 offset:160
	v_fmac_f32_e32 v36, v14, v30
	v_fmac_f32_e32 v36, v15, v31
	v_fmac_f32_e32 v36, v12, v32
	v_fmac_f32_e32 v36, v13, v33
	ds_read_b128 v[30:33], v23 offset:176
	s_waitcnt lgkmcnt(0)
	v_fmac_f32_e32 v36, v10, v26
	v_fmac_f32_e32 v36, v11, v27
	v_fmac_f32_e32 v36, v8, v28
	v_fmac_f32_e32 v36, v9, v29
	v_fmac_f32_e32 v36, v6, v30
	v_fmac_f32_e32 v36, v7, v31
	v_fmac_f32_e32 v36, v4, v32
	v_fmac_f32_e32 v36, v5, v33
	v_mul_f32_e64 v26, |v36|, s6
	v_exp_f32_e32 v26, v26
	v_fmac_f32_e32 v35, 0x3377d1cf, v34
	v_fma_f32 v24, v24, s0, 0
	v_fmac_f32_e32 v35, 0x3f317217, v34
	v_cmp_lt_f32_e64 s[0:1], |v34|, s31
	v_add_f32_e32 v26, 1.0, v26
	v_cndmask_b32_e32 v28, 0, v213, vcc
	v_cndmask_b32_e64 v27, v34, v35, s[0:1]
	v_cmp_gt_f32_e32 vcc, s89, v26
	v_sub_f32_e32 v27, v27, v28
	v_sub_f32_e32 v25, v25, v27
	v_cndmask_b32_e64 v28, 0, 32, vcc
	v_ldexp_f32 v26, v26, v28
	v_log_f32_e32 v34, v26
	ds_read_b128 v[26:29], v23 offset:192
	v_min_f32_e32 v35, 0, v36
	v_fmamk_f32 v25, v25, 0x3d800000, v24
	v_mul_f32_e32 v30, 0x3f317217, v34
	v_fma_f32 v36, v34, s7, -v30
	ds_read_b128 v[30:33], v23 offset:208
	s_waitcnt lgkmcnt(0)
	v_fma_f32 v37, v18, v26, v22
	v_fmac_f32_e32 v37, v19, v27
	v_fmac_f32_e32 v37, v16, v28
	v_fmac_f32_e32 v37, v17, v29
	ds_read_b128 v[26:29], v23 offset:224
	v_fmac_f32_e32 v37, v14, v30
	v_fmac_f32_e32 v37, v15, v31
	v_fmac_f32_e32 v37, v12, v32
	v_fmac_f32_e32 v37, v13, v33
	ds_read_b128 v[30:33], v23 offset:240
	s_waitcnt lgkmcnt(0)
	v_fmac_f32_e32 v37, v10, v26
	v_fmac_f32_e32 v37, v11, v27
	v_fmac_f32_e32 v37, v8, v28
	v_fmac_f32_e32 v37, v9, v29
	v_fmac_f32_e32 v37, v6, v30
	v_fmac_f32_e32 v37, v7, v31
	v_fmac_f32_e32 v37, v4, v32
	v_fmac_f32_e32 v37, v5, v33
	v_mul_f32_e64 v26, |v37|, s6
	v_exp_f32_e32 v26, v26
	v_fmac_f32_e32 v36, 0x3377d1cf, v34
	v_fmac_f32_e32 v36, 0x3f317217, v34
	v_cmp_lt_f32_e64 s[0:1], |v34|, s31
	v_add_f32_e32 v26, 1.0, v26
	v_cndmask_b32_e32 v28, 0, v213, vcc
	v_cndmask_b32_e64 v27, v34, v36, s[0:1]
	v_cmp_gt_f32_e32 vcc, s89, v26
	v_sub_f32_e32 v27, v27, v28
	v_min_f32_e32 v36, 0, v37
	v_cndmask_b32_e64 v28, 0, 32, vcc
	v_ldexp_f32 v26, v26, v28
	v_log_f32_e32 v34, v26
	v_sub_f32_e32 v26, v35, v27
	v_fmamk_f32 v35, v26, 0x3d800000, v25
	ds_read_b128 v[26:29], v23 offset:256
	v_mul_f32_e32 v30, 0x3f317217, v34
	v_fma_f32 v37, v34, s7, -v30
	ds_read_b128 v[30:33], v23 offset:272
	v_fmac_f32_e32 v37, 0x3377d1cf, v34
	s_waitcnt lgkmcnt(0)
	v_fma_f32 v38, v18, v26, v22
	v_fmac_f32_e32 v38, v19, v27
	v_fmac_f32_e32 v38, v16, v28
	v_fmac_f32_e32 v38, v17, v29
	ds_read_b128 v[26:29], v23 offset:288
	v_fmac_f32_e32 v38, v14, v30
	v_fmac_f32_e32 v38, v15, v31
	v_fmac_f32_e32 v38, v12, v32
	v_fmac_f32_e32 v38, v13, v33
	ds_read_b128 v[30:33], v23 offset:304
	s_waitcnt lgkmcnt(0)
	v_fmac_f32_e32 v38, v10, v26
	v_fmac_f32_e32 v38, v11, v27
	v_fmac_f32_e32 v38, v8, v28
	v_fmac_f32_e32 v38, v9, v29
	v_fmac_f32_e32 v38, v6, v30
	v_fmac_f32_e32 v38, v7, v31
	v_fmac_f32_e32 v38, v4, v32
	v_fmac_f32_e32 v38, v5, v33
	v_mul_f32_e64 v26, |v38|, s6
	v_exp_f32_e32 v26, v26
	v_fmac_f32_e32 v37, 0x3f317217, v34
	v_cmp_lt_f32_e64 s[0:1], |v34|, s31
	v_cndmask_b32_e32 v28, 0, v213, vcc
	v_add_f32_e32 v26, 1.0, v26
	v_cndmask_b32_e64 v27, v34, v37, s[0:1]
	v_cmp_gt_f32_e32 vcc, s89, v26
	v_sub_f32_e32 v27, v27, v28
	v_min_f32_e32 v37, 0, v38
	v_cndmask_b32_e64 v28, 0, 32, vcc
	v_ldexp_f32 v26, v26, v28
	v_log_f32_e32 v34, v26
	v_sub_f32_e32 v26, v36, v27
	v_fmamk_f32 v36, v26, 0x3d800000, v35
	ds_read_b128 v[26:29], v23 offset:320
	v_mul_f32_e32 v30, 0x3f317217, v34
	v_fma_f32 v38, v34, s7, -v30
	ds_read_b128 v[30:33], v23 offset:336
	v_fmac_f32_e32 v38, 0x3377d1cf, v34
	s_waitcnt lgkmcnt(0)
	v_fma_f32 v39, v18, v26, v22
	v_fmac_f32_e32 v39, v19, v27
	v_fmac_f32_e32 v39, v16, v28
	v_fmac_f32_e32 v39, v17, v29
	ds_read_b128 v[26:29], v23 offset:352
	v_fmac_f32_e32 v39, v14, v30
	v_fmac_f32_e32 v39, v15, v31
	v_fmac_f32_e32 v39, v12, v32
	v_fmac_f32_e32 v39, v13, v33
	ds_read_b128 v[30:33], v23 offset:368
	s_waitcnt lgkmcnt(0)
	v_fmac_f32_e32 v39, v10, v26
	v_fmac_f32_e32 v39, v11, v27
	v_fmac_f32_e32 v39, v8, v28
	v_fmac_f32_e32 v39, v9, v29
	v_fmac_f32_e32 v39, v6, v30
	v_fmac_f32_e32 v39, v7, v31
	v_fmac_f32_e32 v39, v4, v32
	v_fmac_f32_e32 v39, v5, v33
	v_mul_f32_e64 v26, |v39|, s6
	v_exp_f32_e32 v26, v26
	v_fmac_f32_e32 v38, 0x3f317217, v34
	v_cmp_lt_f32_e64 s[0:1], |v34|, s31
	v_cndmask_b32_e32 v28, 0, v213, vcc
	v_add_f32_e32 v26, 1.0, v26
	v_cndmask_b32_e64 v27, v34, v38, s[0:1]
	v_cmp_gt_f32_e32 vcc, s89, v26
	v_sub_f32_e32 v27, v27, v28
	v_min_f32_e32 v38, 0, v39
	v_cndmask_b32_e64 v28, 0, 32, vcc
	v_ldexp_f32 v26, v26, v28
	v_log_f32_e32 v34, v26
	v_sub_f32_e32 v26, v37, v27
	v_fmamk_f32 v37, v26, 0x3d800000, v36
	ds_read_b128 v[26:29], v23 offset:384
	v_mul_f32_e32 v30, 0x3f317217, v34
	v_fma_f32 v39, v34, s7, -v30
	ds_read_b128 v[30:33], v23 offset:400
	v_fmac_f32_e32 v39, 0x3377d1cf, v34
	s_waitcnt lgkmcnt(0)
	v_fma_f32 v40, v18, v26, v22
	v_fmac_f32_e32 v40, v19, v27
	v_fmac_f32_e32 v40, v16, v28
	v_fmac_f32_e32 v40, v17, v29
	ds_read_b128 v[26:29], v23 offset:416
	v_fmac_f32_e32 v40, v14, v30
	v_fmac_f32_e32 v40, v15, v31
	v_fmac_f32_e32 v40, v12, v32
	v_fmac_f32_e32 v40, v13, v33
	ds_read_b128 v[30:33], v23 offset:432
	s_waitcnt lgkmcnt(0)
	v_fmac_f32_e32 v40, v10, v26
	v_fmac_f32_e32 v40, v11, v27
	v_fmac_f32_e32 v40, v8, v28
	v_fmac_f32_e32 v40, v9, v29
	v_fmac_f32_e32 v40, v6, v30
	v_fmac_f32_e32 v40, v7, v31
	v_fmac_f32_e32 v40, v4, v32
	v_fmac_f32_e32 v40, v5, v33
	v_mul_f32_e64 v26, |v40|, s6
	v_exp_f32_e32 v26, v26
	v_fmac_f32_e32 v39, 0x3f317217, v34
	v_cmp_lt_f32_e64 s[0:1], |v34|, s31
	v_cndmask_b32_e32 v28, 0, v213, vcc
	v_add_f32_e32 v26, 1.0, v26
	v_cndmask_b32_e64 v27, v34, v39, s[0:1]
	v_cmp_gt_f32_e32 vcc, s89, v26
	v_sub_f32_e32 v27, v27, v28
	v_min_f32_e32 v39, 0, v40
	v_cndmask_b32_e64 v28, 0, 32, vcc
	v_ldexp_f32 v26, v26, v28
	v_log_f32_e32 v34, v26
	v_sub_f32_e32 v26, v38, v27
	v_fmamk_f32 v38, v26, 0x3d800000, v37
	ds_read_b128 v[26:29], v23 offset:448
	v_mul_f32_e32 v30, 0x3f317217, v34
	v_fma_f32 v40, v34, s7, -v30
	ds_read_b128 v[30:33], v23 offset:464
	v_fmac_f32_e32 v40, 0x3377d1cf, v34
	s_waitcnt lgkmcnt(0)
	v_fmac_f32_e32 v22, v18, v26
	v_fmac_f32_e32 v22, v19, v27
	v_fmac_f32_e32 v22, v16, v28
	v_fmac_f32_e32 v22, v17, v29
	ds_read_b128 v[16:19], v23 offset:480
	v_fmac_f32_e32 v22, v14, v30
	v_fmac_f32_e32 v22, v15, v31
	v_fmac_f32_e32 v22, v12, v32
	v_fmac_f32_e32 v22, v13, v33
	ds_read_b128 v[12:15], v23 offset:496
	s_waitcnt lgkmcnt(0)
	v_fmac_f32_e32 v22, v10, v16
	v_fmac_f32_e32 v22, v11, v17
	v_fmac_f32_e32 v22, v8, v18
	v_fmac_f32_e32 v22, v9, v19
	v_fmac_f32_e32 v22, v6, v12
	v_fmac_f32_e32 v22, v7, v13
	v_fmac_f32_e32 v22, v4, v14
	v_fmac_f32_e32 v22, v5, v15
	v_mul_f32_e64 v4, |v22|, s6
	v_exp_f32_e32 v4, v4
	v_fmac_f32_e32 v40, 0x3f317217, v34
	v_cmp_lt_f32_e64 s[0:1], |v34|, s31
	v_cndmask_b32_e32 v6, 0, v213, vcc
	v_add_f32_e32 v4, 1.0, v4
	v_cndmask_b32_e64 v5, v34, v40, s[0:1]
	v_cmp_gt_f32_e32 vcc, s89, v4
	v_sub_f32_e32 v5, v5, v6
	v_sub_f32_e32 v5, v39, v5
	v_cndmask_b32_e64 v6, 0, 32, vcc
	v_ldexp_f32 v4, v4, v6
	v_log_f32_e32 v4, v4
	v_fmamk_f32 v12, v5, 0x3d800000, v38
	v_min_f32_e32 v5, 0, v22
	s_movk_i32 s6, 0x4080
	v_mul_f32_e32 v6, 0x3f317217, v4
	v_fma_f32 v6, v4, s7, -v6
	v_fmac_f32_e32 v6, 0x3377d1cf, v4
	v_fmac_f32_e32 v6, 0x3f317217, v4
	v_cmp_lt_f32_e64 s[0:1], |v4|, s31
	s_movk_i32 s7, 0x90
	s_nop 0
	v_cndmask_b32_e64 v4, v4, v6, s[0:1]
	v_cndmask_b32_e32 v6, 0, v213, vcc
	v_sub_f32_e32 v4, v4, v6
	v_sub_f32_e32 v4, v5, v4
	v_fmamk_f32 v13, v4, 0x3d800000, v12
	ds_write_b32 v21, v13 offset:8448
	s_waitcnt lgkmcnt(0)
	s_barrier
	ds_read2st64_b32 v[4:5], v2 offset0:33 offset1:34
	ds_read2st64_b32 v[6:7], v2 offset0:35 offset1:36
	ds_read2st64_b32 v[8:9], v2 offset0:37 offset1:38
	ds_read2st64_b32 v[10:11], v2 offset0:39 offset1:40
	v_cmp_lt_i32_e32 vcc, 0, v3
	s_waitcnt lgkmcnt(0)
	v_add_f32_e32 v4, 0, v4
	s_movk_i32 s0, 0x820
	v_cndmask_b32_e32 v4, 0, v4, vcc
	v_cmp_lt_i32_e32 vcc, 1, v3
	s_nop 1
	v_cndmask_b32_e32 v5, 0, v5, vcc
	v_cmp_lt_i32_e32 vcc, 2, v3
	v_add_f32_e32 v4, v4, v5
	s_nop 0
	v_cndmask_b32_e32 v5, 0, v6, vcc
	v_cmp_lt_i32_e32 vcc, 3, v3
	v_add_f32_e32 v4, v4, v5
	s_nop 0
	v_cndmask_b32_e32 v5, 0, v7, vcc
	v_cmp_lt_i32_e32 vcc, 4, v3
	v_add_f32_e32 v4, v4, v5
	s_nop 0
	v_cndmask_b32_e32 v5, 0, v8, vcc
	v_cmp_lt_i32_e32 vcc, 5, v3
	v_add_f32_e32 v4, v4, v5
	s_nop 0
	v_cndmask_b32_e32 v5, 0, v9, vcc
	v_cmp_lt_i32_e32 vcc, 6, v3
	v_add_f32_e32 v4, v4, v5
	s_nop 0
	v_cndmask_b32_e32 v5, 0, v10, vcc
	v_cmp_lt_i32_e32 vcc, 7, v3
	v_add_f32_e32 v4, v4, v5
	v_mad_u64_u32 v[2:3], s[0:1], v3, s0, v[2:3]
	v_cndmask_b32_e32 v5, 0, v11, vcc
	v_add_f32_e32 v4, v4, v5
	v_add_f32_e32 v5, v24, v4
	v_add_f32_e32 v3, v25, v4
	v_add_u32_e32 v6, 0x2800, v2
	ds_write2_b32 v6, v5, v3 offset0:64 offset1:129
	v_add_f32_e32 v3, v35, v4
	v_add_f32_e32 v5, v36, v4
	v_add_u32_e32 v6, 0x2a00, v2
	ds_write2_b32 v6, v3, v5 offset0:66 offset1:131
	v_add_f32_e32 v3, v37, v4
	v_add_f32_e32 v5, v38, v4
	v_add_u32_e32 v6, 0x2c00, v2
	ds_write2_b32 v6, v3, v5 offset0:68 offset1:133
	v_add_f32_e32 v3, v12, v4
	v_add_f32_e32 v4, v13, v4
	v_add_u32_e32 v2, 0x2e00, v2
	ds_write2_b32 v2, v3, v4 offset0:70 offset1:135
	s_lshl_b64 s[0:1], s[44:45], 10
	v_lshlrev_b32_e32 v2, 3, v20
	s_add_u32 s0, s2, s0
	v_and_b32_e32 v15, 56, v2
	s_addc_u32 s1, s14, s1
	v_lshlrev_b32_e32 v10, 2, v15
	v_lshl_add_u64 v[6:7], v[0:1], 2, s[0:1]
	v_ashrrev_i32_e32 v12, 3, v20
	v_add_u32_e32 v14, 0, v10
	s_movk_i32 s0, 0x104
	v_mad_u64_u32 v[16:17], s[0:1], v12, s0, v[14:15]
	v_add_u32_e32 v2, 0x2900, v16
	v_add_u32_e32 v4, 0x2908, v16
	v_ashrrev_i32_e32 v13, 31, v12
	s_waitcnt lgkmcnt(0)
	s_barrier
	ds_read2_b32 v[2:3], v2 offset1:1
	ds_read2_b32 v[4:5], v4 offset1:1
	v_add_u32_e32 v21, 0x2918, v16
	v_lshlrev_b64 v[18:19], 10, v[12:13]
	v_add_u32_e32 v17, 0x2910, v16
	ds_read2_b32 v[8:9], v21 offset1:1
	v_lshl_add_u64 v[6:7], v[6:7], 0, v[18:19]
	v_mov_b32_e32 v11, v1
	v_lshl_add_u64 v[10:11], v[6:7], 0, v[10:11]
	ds_read2_b32 v[6:7], v17 offset1:1
	ds_read_b32 v13, v16 offset:10516
	s_waitcnt lgkmcnt(0)
	global_store_dwordx4 v[10:11], v[2:5], off
	v_add_u32_e32 v18, 0x68fc, v14
	ds_read2_b32 v[16:17], v21 offset1:1
	ds_read2_b32 v[18:19], v18 offset1:1
	global_store_dwordx4 v[10:11], v[6:9], off offset:16
	v_lshlrev_b32_e32 v10, 1, v15
	v_mov_b32_e32 v11, v1
	v_mov_b64_e32 v[8:9], s[46:47]
	v_mad_i64_i32 v[8:9], s[0:1], v12, s59, v[8:9]
	v_lshl_add_u64 v[8:9], v[0:1], 1, v[8:9]
	v_lshl_add_u64 v[8:9], v[8:9], 0, v[10:11]
	v_add_co_u32_e32 v8, vcc, s61, v8
	s_waitcnt lgkmcnt(0)
	v_sub_f32_e32 v2, v18, v2
	v_addc_co_u32_e32 v9, vcc, 0, v9, vcc
	s_waitcnt vmcnt(2)
	v_mov_b32_e32 v8, v100
	v_mov_b32_e32 v9, v101
	v_mov_b32_e32 v10, v102
	v_mov_b32_e32 v11, v103
	v_mul_f32_e32 v2, 0x3fb8aa3b, v2
	v_exp_f32_e32 v2, v2
	v_sub_f32_e32 v3, v19, v3
	v_mul_f32_e32 v3, 0x3fb8aa3b, v3
	v_add_u32_e32 v7, 0x6904, v14
	v_exp_f32_e32 v3, v3
	ds_read2_b32 v[22:23], v7 offset1:1
	v_lshlrev_b32_e32 v12, 1, v12
	v_cmp_gt_i32_e32 vcc, 64, v20
	s_nop 0
	v_lshlrev_b32_e32 v7, 16, v8
	v_mul_f32_e32 v2, v2, v7
	v_mul_u32_u24_e32 v7, 0x90, v15
	v_and_b32_e32 v8, 0xffff0000, v8
	v_cvt_pk_bf16_f32 v2, v2, s0
	v_add3_u32 v7, 0, v12, v7
	ds_write_b16 v7, v2 offset:64512
	v_mul_f32_e32 v2, v3, v8
	v_cvt_pk_bf16_f32 v2, v2, s0
	ds_write_b16 v7, v2 offset:64656
	s_waitcnt lgkmcnt(2)
	v_sub_f32_e32 v2, v22, v4
	v_mul_f32_e32 v2, 0x3fb8aa3b, v2
	v_exp_f32_e32 v2, v2
	v_sub_f32_e32 v3, v23, v5
	v_mul_f32_e32 v3, 0x3fb8aa3b, v3
	v_lshlrev_b32_e32 v21, 16, v9
	v_exp_f32_e32 v3, v3
	v_mul_f32_e32 v2, v2, v21
	v_cvt_pk_bf16_f32 v2, v2, s0
	v_and_b32_e32 v9, 0xffff0000, v9
	ds_write_b16 v7, v2 offset:64800
	v_add_u32_e32 v2, 0x690c, v14
	v_mul_f32_e32 v4, v3, v9
	ds_read2_b32 v[2:3], v2 offset1:1
	v_cvt_pk_bf16_f32 v4, v4, s0
	ds_write_b16 v7, v4 offset:64944
	v_add_u32_e32 v4, 0x6914, v14
	ds_read2_b32 v[4:5], v4 offset1:1
	s_waitcnt lgkmcnt(2)
	v_sub_f32_e32 v2, v2, v6
	v_mul_f32_e32 v2, 0x3fb8aa3b, v2
	v_exp_f32_e32 v2, v2
	v_sub_f32_e32 v3, v3, v13
	v_mul_f32_e32 v3, 0x3fb8aa3b, v3
	v_exp_f32_e32 v3, v3
	v_lshlrev_b32_e32 v24, 16, v10
	v_mul_f32_e32 v2, v2, v24
	v_and_b32_e32 v10, 0xffff0000, v10
	v_cvt_pk_bf16_f32 v2, v2, s0
	ds_write_b16 v7, v2 offset:65088
	v_mul_f32_e32 v2, v3, v10
	v_cvt_pk_bf16_f32 v2, v2, s0
	ds_write_b16 v7, v2 offset:65232
	s_waitcnt lgkmcnt(2)
	v_sub_f32_e32 v2, v4, v16
	v_mul_f32_e32 v2, 0x3fb8aa3b, v2
	v_exp_f32_e32 v2, v2
	v_sub_f32_e32 v3, v5, v17
	v_mul_f32_e32 v3, 0x3fb8aa3b, v3
	v_exp_f32_e32 v3, v3
	v_lshlrev_b32_e32 v18, 16, v11
	v_mul_f32_e32 v2, v2, v18
	v_and_b32_e32 v11, 0xffff0000, v11
	v_cvt_pk_bf16_f32 v2, v2, s0
	ds_write_b16 v7, v2 offset:65376
	v_mul_f32_e32 v2, v3, v11
	v_cvt_pk_bf16_f32 v2, v2, s0
	s_lshl_b32 s0, s25, 7
	v_mov_b32_e32 v8, v204
	s_or_b32 s25, s0, 0x400
	s_lshl_b64 s[0:1], s[44:45], 1
	ds_write_b16 v7, v2 offset:65520
	s_add_u32 s0, s8, s0
	v_lshlrev_b32_e32 v2, 4, v8
	s_addc_u32 s1, s9, s1
	v_and_b32_e32 v10, 0x70, v2
	v_mov_b32_e32 v11, v1
	v_lshl_add_u64 v[6:7], s[0:1], 0, v[10:11]
	v_ashrrev_i32_e32 v11, 3, v8
	v_add_u32_e32 v8, 0x200, v8
	v_add_u32_e32 v2, s25, v11
	v_ashrrev_i32_e32 v14, 3, v8
	v_mad_i64_i32 v[2:3], s[0:1], v2, s6, v[6:7]
	v_add_u32_e32 v8, s25, v14
	s_nop 0
	v_mad_i64_i32 v[6:7], s[0:1], v8, s6, v[6:7]
	s_nop 0
	v_readlane_b32 s0, v236, 32
	s_movk_i32 s6, 0x90
	s_nop 0
	v_add_u32_e32 v10, s0, v10
	v_mad_u64_u32 v[12:13], s[0:1], v11, s7, v[10:11]
	s_waitcnt vmcnt(2)
	ds_write_b128 v12, v[104:107]
	v_mad_u64_u32 v[2:3], s[0:1], v14, s7, v[10:11]
	s_nop 0
	ds_write_b128 v2, v[108:111]
	s_and_saveexec_b64 s[0:1], vcc
	s_cbranch_execz .LBB0_411
	s_lshl_b32 s24, s24, 8
	v_add3_u32 v2, v20, s24, v0
	v_lshl_add_u32 v0, v20, 2, 0
	ds_read_b32 v0, v0 offset:26876
	v_ashrrev_i32_e32 v3, 31, v2
	v_lshl_add_u64 v[2:3], v[2:3], 2, s[18:19]
	s_waitcnt lgkmcnt(0)
	v_mul_f32_e32 v0, 0x3fb8aa3b, v0
	v_exp_f32_e32 v0, v0
	global_store_dword v[2:3], v0, off
	s_branch .LBB0_411
